# GEMM K-loops: MFMA order changed so both k-steps of each accumulator issue back-to-back (snake over m,n)
# speedup vs baseline: 1.0107x; 1.0107x over previous
; #define PG8_STAGE(bufoff, gbase, voff) do { _Pragma("unroll") for (int _i = 0; _i < 2; ++_i) \
;         __builtin_amdgcn_global_load_lds((const unsigned*)((const char*)(gbase) + (voff)[_i]), (PG8_LAS unsigned*)(lds + (bufoff) + ldsw + _i * 8192), 16, 0, 0); } while (0)
; #define PG8_LDA(dst, b, h) do { _Pragma("unroll") for (int m = 0; m < 4; ++m) _Pragma("unroll") for (int k = 0; k < 2; ++k) dst[m][k] = *(const PG8_LAS bf16x8*)(lds + PG8_SA(b, h) + aoff + m * 2048 + k * 1024); } while (0)
; #define PG8_LDB(dst, b, h) do { _Pragma("unroll") for (int n = 0; n < 2; ++n) _Pragma("unroll") for (int k = 0; k < 2; ++k) dst[n][k] = *(const PG8_LAS bf16x8*)(lds + PG8_SB(b, h) + boff + n * 2048 + k * 1024); } while (0)
; #define PG8_MMA(ai, bj, At, Bt) do { __builtin_amdgcn_s_setprio(1); _Pragma("unroll") for (int m = 0; m < 4; ++m) _Pragma("unroll") for (int n = 0; n < 2; ++n) _Pragma("unroll") for (int k = 0; k < 2; ++k) \
;         acc[ai][bj][m][n] = __builtin_amdgcn_mfma_f32_16x16x32_bf16(Bt[n][k], At[m][k], acc[ai][bj][m][n], 0, 0, 0); __builtin_amdgcn_s_setprio(0); } while (0)
; #define PG8_WAIT_V(n) asm volatile("s_waitcnt vmcnt(" #n ")" ::: "memory")
; #define PG8_WAIT_L(n) asm volatile("s_waitcnt lgkmcnt(" #n ")" ::: "memory")
; template <class Epi, class Sched, bool ALIGN_EPI = false, bool SP2 = false>
; __device__ __forceinline__ void gemm_phase(PG8_LAS unsigned char* lds, const Gemm g, const Sched& S, const Epi& E) {
;     ...
;             const bool last = (t == nt - 2);
;             const char* a1 = cA + (size_t)(t + 1) * kstep;
;             const char* a2 = last ? nA : cA + (size_t)(t + 2) * kstep; const char* b2 = last ? nB : cB + (size_t)(t + 2) * kstep;
;             const char* a3 = a2 + kstep; const char* b3 = b2 + kstep;
;             if (last && has_next) S.a_ready(nxt);
;             if constexpr (SP2) {
;             PG8_LDB(B0, 0, 0); PG8_LDB(B1, 0, 1); PG8_SCHED; PG8_LDA(At, 0, 0); PG8_STAGE(PG8_SA(1, 1), a1 + hstep, voffA);
;             PG8_WAIT_V(8); PG8_WAIT_L(0); PG8_BAR; PG8_MMA(0, 0, At, B0); PG8_MMA(0, 1, At, B1); PG8_BAR; PG8_SCHED;
;             PG8_LDA(At, 0, 1); PG8_STAGE(PG8_SB(0, 0), b2, voffB); PG8_STAGE(PG8_SB(0, 1), b2 + hstep, voffB); PG8_STAGE(PG8_SA(0, 0), a2, voffA);
;             PG8_WAIT_V(8); PG8_WAIT_L(0); PG8_BAR; PG8_MMA(1, 0, At, B0); PG8_MMA(1, 1, At, B1); PG8_BAR; PG8_SCHED;
.LBB0_102:
	ds_read_b128 v[160:163], v155
	ds_read_b128 v[164:167], v155 offset:1024
	ds_read_b128 v[168:171], v155 offset:2048
	ds_read_b128 v[172:175], v155 offset:3072
	ds_read_b128 v[176:179], v157
	ds_read_b128 v[180:183], v157 offset:1024
	ds_read_b128 v[184:187], v157 offset:2048
	ds_read_b128 v[188:191], v157 offset:3072
	s_add_u32 s62, s74, 0xfff80080
	s_addc_u32 s63, s75, -1
	s_cmp_eq_u32 s90, 28
	s_cselect_b32 s79, s10, s63
	s_cselect_b32 s78, s11, s62
	s_cselect_b32 s77, s51, s89
	s_cselect_b32 s76, s55, s88
	v_lshl_add_u64 v[224:225], s[74:75], 0, v[138:139]
	s_add_i32 m0, s61, 0xc000
	ds_read_b128 v[192:195], v159
	ds_read_b128 v[196:199], v159 offset:1024
	ds_read_b128 v[200:203], v159 offset:2048
	ds_read_b128 v[204:207], v159 offset:3072
	ds_read_b128 v[208:211], v159 offset:4096
	ds_read_b128 v[212:215], v159 offset:5120
	ds_read_b128 v[216:219], v159 offset:6144
	ds_read_b128 v[220:223], v159 offset:7168
	global_load_lds_dwordx4 v[224:225], off
	v_lshl_add_u64 v[224:225], s[74:75], 0, v[140:141]
	s_add_i32 m0, s61, 0xe000
	s_nop 0
	global_load_lds_dwordx4 v[224:225], off
	s_waitcnt vmcnt(8)
	s_waitcnt lgkmcnt(0)
	s_barrier
	s_setprio 1
	s_waitcnt lgkmcnt(0)
	v_mfma_f32_16x16x32_bf16 v[124:127], v[160:163], v[192:195], v[124:127]
	v_mfma_f32_16x16x32_bf16 v[124:127], v[164:167], v[196:199], v[124:127]
	v_mfma_f32_16x16x32_bf16 v[120:123], v[168:171], v[192:195], v[120:123]
	v_mfma_f32_16x16x32_bf16 v[120:123], v[172:175], v[196:199], v[120:123]
	v_mfma_f32_16x16x32_bf16 v[104:107], v[168:171], v[200:203], v[104:107]
	v_mfma_f32_16x16x32_bf16 v[104:107], v[172:175], v[204:207], v[104:107]
	v_mfma_f32_16x16x32_bf16 v[108:111], v[160:163], v[200:203], v[108:111]
	v_mfma_f32_16x16x32_bf16 v[108:111], v[164:167], v[204:207], v[108:111]
	v_mfma_f32_16x16x32_bf16 v[92:95], v[160:163], v[208:211], v[92:95]
	v_mfma_f32_16x16x32_bf16 v[92:95], v[164:167], v[212:215], v[92:95]
	v_mfma_f32_16x16x32_bf16 v[88:91], v[168:171], v[208:211], v[88:91]
	v_mfma_f32_16x16x32_bf16 v[88:91], v[172:175], v[212:215], v[88:91]
	v_mfma_f32_16x16x32_bf16 v[72:75], v[168:171], v[216:219], v[72:75]
	v_mfma_f32_16x16x32_bf16 v[72:75], v[172:175], v[220:223], v[72:75]
	v_mfma_f32_16x16x32_bf16 v[76:79], v[160:163], v[216:219], v[76:79]
	v_mfma_f32_16x16x32_bf16 v[76:79], v[164:167], v[220:223], v[76:79]
	s_setprio 0
	s_setprio 1
	v_mfma_f32_16x16x32_bf16 v[116:119], v[176:179], v[192:195], v[116:119]
	v_mfma_f32_16x16x32_bf16 v[116:119], v[180:183], v[196:199], v[116:119]
	v_mfma_f32_16x16x32_bf16 v[112:115], v[184:187], v[192:195], v[112:115]
	v_mfma_f32_16x16x32_bf16 v[112:115], v[188:191], v[196:199], v[112:115]
	v_mfma_f32_16x16x32_bf16 v[96:99], v[184:187], v[200:203], v[96:99]
	v_mfma_f32_16x16x32_bf16 v[96:99], v[188:191], v[204:207], v[96:99]
	v_mfma_f32_16x16x32_bf16 v[100:103], v[176:179], v[200:203], v[100:103]
	v_mfma_f32_16x16x32_bf16 v[100:103], v[180:183], v[204:207], v[100:103]
	v_mfma_f32_16x16x32_bf16 v[84:87], v[176:179], v[208:211], v[84:87]
	v_mfma_f32_16x16x32_bf16 v[84:87], v[180:183], v[212:215], v[84:87]
	v_mfma_f32_16x16x32_bf16 v[80:83], v[184:187], v[208:211], v[80:83]
	v_mfma_f32_16x16x32_bf16 v[80:83], v[188:191], v[212:215], v[80:83]
	v_mfma_f32_16x16x32_bf16 v[64:67], v[184:187], v[216:219], v[64:67]
	v_mfma_f32_16x16x32_bf16 v[64:67], v[188:191], v[220:223], v[64:67]
	v_mfma_f32_16x16x32_bf16 v[68:71], v[176:179], v[216:219], v[68:71]
	v_mfma_f32_16x16x32_bf16 v[68:71], v[180:183], v[220:223], v[68:71]
	s_setprio 0
	s_barrier
	s_add_i32 s62, s84, s35
	v_lshl_add_u64 v[224:225], s[76:77], 0, v[130:131]
	s_mov_b32 m0, s62
	ds_read_b128 v[192:195], v159 offset:16384
	ds_read_b128 v[196:199], v159 offset:17408
	ds_read_b128 v[200:203], v159 offset:18432
	ds_read_b128 v[204:207], v159 offset:19456
	ds_read_b128 v[208:211], v159 offset:20480
	ds_read_b128 v[212:215], v159 offset:21504
	ds_read_b128 v[216:219], v159 offset:22528
	ds_read_b128 v[220:223], v159 offset:23552
	global_load_lds_dwordx4 v[224:225], off
	s_add_i32 m0, s62, 0x2000
	s_add_u32 s92, s76, 0x80000
	v_lshl_add_u64 v[226:227], s[76:77], 0, v[134:135]
	s_addc_u32 s93, s77, 0
	s_add_i32 s62, s85, s35
	global_load_lds_dwordx4 v[226:227], off
	v_lshl_add_u64 v[228:229], s[92:93], 0, v[130:131]
	s_mov_b32 m0, s62
	v_lshl_add_u64 v[230:231], s[78:79], 0, v[132:133]
	global_load_lds_dwordx4 v[228:229], off
	v_lshl_add_u64 v[228:229], s[92:93], 0, v[134:135]
	s_add_i32 m0, s62, 0x2000
	s_nop 0
	global_load_lds_dwordx4 v[228:229], off
	v_lshl_add_u64 v[228:229], s[78:79], 0, v[128:129]
	s_mov_b32 m0, s61
	s_nop 0
	global_load_lds_dwordx4 v[228:229], off
	s_mov_b32 m0, s65
	s_nop 0
	global_load_lds_dwordx4 v[230:231], off
	s_waitcnt vmcnt(8)
	s_waitcnt lgkmcnt(0)
	s_barrier
; #define PG8_STAGE(bufoff, gbase, voff) do { _Pragma("unroll") for (int _i = 0; _i < 2; ++_i) \
;         __builtin_amdgcn_global_load_lds((const unsigned*)((const char*)(gbase) + (voff)[_i]), (PG8_LAS unsigned*)(lds + (bufoff) + ldsw + _i * 8192), 16, 0, 0); } while (0)
; #define PG8_LDA(dst, b, h) do { _Pragma("unroll") for (int m = 0; m < 4; ++m) _Pragma("unroll") for (int k = 0; k < 2; ++k) dst[m][k] = *(const PG8_LAS bf16x8*)(lds + PG8_SA(b, h) + aoff + m * 2048 + k * 1024); } while (0)
; #define PG8_LDB(dst, b, h) do { _Pragma("unroll") for (int n = 0; n < 2; ++n) _Pragma("unroll") for (int k = 0; k < 2; ++k) dst[n][k] = *(const PG8_LAS bf16x8*)(lds + PG8_SB(b, h) + boff + n * 2048 + k * 1024); } while (0)
; #define PG8_MMA(ai, bj, At, Bt) do { __builtin_amdgcn_s_setprio(1); _Pragma("unroll") for (int m = 0; m < 4; ++m) _Pragma("unroll") for (int n = 0; n < 2; ++n) _Pragma("unroll") for (int k = 0; k < 2; ++k) \
;         acc[ai][bj][m][n] = __builtin_amdgcn_mfma_f32_16x16x32_bf16(Bt[n][k], At[m][k], acc[ai][bj][m][n], 0, 0, 0); __builtin_amdgcn_s_setprio(0); } while (0)
; #define PG8_WAIT_V(n) asm volatile("s_waitcnt vmcnt(" #n ")" ::: "memory")
; #define PG8_WAIT_L(n) asm volatile("s_waitcnt lgkmcnt(" #n ")" ::: "memory")
; #define PG8_BAR __builtin_amdgcn_s_barrier()
; #define PG8_SCHED __builtin_amdgcn_sched_barrier(0)
; template <class Epi, class Sched, bool ALIGN_EPI = false, bool SP2 = false>
; __device__ __forceinline__ void gemm_phase(PG8_LAS unsigned char* lds, const Gemm g, const Sched& S, const Epi& E) {
;     ...
;             PG8_WAIT_V(8); PG8_WAIT_L(0); PG8_BAR; PG8_MMA(1, 0, At, B0); PG8_MMA(1, 1, At, B1); PG8_BAR; PG8_SCHED;
;             PG8_LDB(B0, 1, 0); PG8_LDB(B1, 1, 1); PG8_SCHED; PG8_LDA(At, 1, 0); PG8_STAGE(PG8_SA(0, 1), a2 + hstep, voffA);
;             PG8_WAIT_V(8); PG8_WAIT_L(0); PG8_BAR; PG8_MMA(0, 0, At, B0); PG8_MMA(0, 1, At, B1); PG8_BAR; PG8_SCHED;
	s_setprio 1
	s_waitcnt lgkmcnt(0)
	v_mfma_f32_16x16x32_bf16 v[60:63], v[160:163], v[192:195], v[60:63]
	v_mfma_f32_16x16x32_bf16 v[60:63], v[164:167], v[196:199], v[60:63]
	v_mfma_f32_16x16x32_bf16 v[56:59], v[168:171], v[192:195], v[56:59]
	v_mfma_f32_16x16x32_bf16 v[56:59], v[172:175], v[196:199], v[56:59]
	v_mfma_f32_16x16x32_bf16 v[40:43], v[168:171], v[200:203], v[40:43]
	v_mfma_f32_16x16x32_bf16 v[40:43], v[172:175], v[204:207], v[40:43]
	v_mfma_f32_16x16x32_bf16 v[44:47], v[160:163], v[200:203], v[44:47]
	v_mfma_f32_16x16x32_bf16 v[44:47], v[164:167], v[204:207], v[44:47]
	v_mfma_f32_16x16x32_bf16 v[28:31], v[160:163], v[208:211], v[28:31]
	v_mfma_f32_16x16x32_bf16 v[28:31], v[164:167], v[212:215], v[28:31]
	v_mfma_f32_16x16x32_bf16 v[24:27], v[168:171], v[208:211], v[24:27]
	v_mfma_f32_16x16x32_bf16 v[24:27], v[172:175], v[212:215], v[24:27]
	v_mfma_f32_16x16x32_bf16 v[8:11], v[168:171], v[216:219], v[8:11]
	v_mfma_f32_16x16x32_bf16 v[8:11], v[172:175], v[220:223], v[8:11]
	v_mfma_f32_16x16x32_bf16 v[12:15], v[160:163], v[216:219], v[12:15]
	v_mfma_f32_16x16x32_bf16 v[12:15], v[164:167], v[220:223], v[12:15]
	s_setprio 0
	s_setprio 1
	v_mfma_f32_16x16x32_bf16 v[52:55], v[176:179], v[192:195], v[52:55]
	v_mfma_f32_16x16x32_bf16 v[52:55], v[180:183], v[196:199], v[52:55]
	v_mfma_f32_16x16x32_bf16 v[48:51], v[184:187], v[192:195], v[48:51]
	v_mfma_f32_16x16x32_bf16 v[48:51], v[188:191], v[196:199], v[48:51]
	v_mfma_f32_16x16x32_bf16 v[32:35], v[184:187], v[200:203], v[32:35]
	v_mfma_f32_16x16x32_bf16 v[32:35], v[188:191], v[204:207], v[32:35]
	v_mfma_f32_16x16x32_bf16 v[36:39], v[176:179], v[200:203], v[36:39]
	v_mfma_f32_16x16x32_bf16 v[36:39], v[180:183], v[204:207], v[36:39]
	v_mfma_f32_16x16x32_bf16 v[20:23], v[176:179], v[208:211], v[20:23]
	v_mfma_f32_16x16x32_bf16 v[20:23], v[180:183], v[212:215], v[20:23]
	v_mfma_f32_16x16x32_bf16 v[16:19], v[184:187], v[208:211], v[16:19]
	v_mfma_f32_16x16x32_bf16 v[16:19], v[188:191], v[212:215], v[16:19]
	v_mfma_f32_16x16x32_bf16 v[0:3], v[184:187], v[216:219], v[0:3]
	v_mfma_f32_16x16x32_bf16 v[0:3], v[188:191], v[220:223], v[0:3]
	v_mfma_f32_16x16x32_bf16 v[4:7], v[176:179], v[216:219], v[4:7]
	v_mfma_f32_16x16x32_bf16 v[4:7], v[180:183], v[220:223], v[4:7]
	s_setprio 0
	s_barrier
	s_add_i32 s62, 0, 0x18000
	s_add_i32 s63, 0, 0x1c000
	v_add_u32_e32 v172, s62, v147
	v_add_u32_e32 v188, s63, v147
	ds_read_b128 v[160:163], v172
	ds_read_b128 v[164:167], v172 offset:1024
	ds_read_b128 v[168:171], v172 offset:2048
	ds_read_b128 v[172:175], v172 offset:3072
	ds_read_b128 v[176:179], v188
	ds_read_b128 v[180:183], v188 offset:1024
	ds_read_b128 v[184:187], v188 offset:2048
	ds_read_b128 v[188:191], v188 offset:3072
	s_add_u32 s78, s78, 0x80000
	s_addc_u32 s79, s79, 0
	s_mov_b32 m0, s66
	v_lshl_add_u64 v[232:233], s[78:79], 0, v[128:129]
	ds_read_b128 v[192:195], v159 offset:32768
	ds_read_b128 v[196:199], v159 offset:33792
	ds_read_b128 v[200:203], v159 offset:34816
	ds_read_b128 v[204:207], v159 offset:35840
	ds_read_b128 v[208:211], v159 offset:36864
	ds_read_b128 v[212:215], v159 offset:37888
	ds_read_b128 v[216:219], v159 offset:38912
	ds_read_b128 v[220:223], v159 offset:39936
	global_load_lds_dwordx4 v[232:233], off
	v_lshl_add_u64 v[232:233], s[78:79], 0, v[132:133]
	s_mov_b32 m0, s67
	s_nop 0
	global_load_lds_dwordx4 v[232:233], off
	s_waitcnt vmcnt(8)
	s_waitcnt lgkmcnt(0)
	s_barrier
	s_setprio 1
	s_waitcnt lgkmcnt(0)
	v_mfma_f32_16x16x32_bf16 v[124:127], v[160:163], v[192:195], v[124:127]
	v_mfma_f32_16x16x32_bf16 v[124:127], v[164:167], v[196:199], v[124:127]
	v_mfma_f32_16x16x32_bf16 v[120:123], v[168:171], v[192:195], v[120:123]
	v_mfma_f32_16x16x32_bf16 v[120:123], v[172:175], v[196:199], v[120:123]
	v_mfma_f32_16x16x32_bf16 v[104:107], v[168:171], v[200:203], v[104:107]
	v_mfma_f32_16x16x32_bf16 v[104:107], v[172:175], v[204:207], v[104:107]
	v_mfma_f32_16x16x32_bf16 v[108:111], v[160:163], v[200:203], v[108:111]
	v_mfma_f32_16x16x32_bf16 v[108:111], v[164:167], v[204:207], v[108:111]
	v_mfma_f32_16x16x32_bf16 v[92:95], v[160:163], v[208:211], v[92:95]
	v_mfma_f32_16x16x32_bf16 v[92:95], v[164:167], v[212:215], v[92:95]
	v_mfma_f32_16x16x32_bf16 v[88:91], v[168:171], v[208:211], v[88:91]
	v_mfma_f32_16x16x32_bf16 v[88:91], v[172:175], v[212:215], v[88:91]
	v_mfma_f32_16x16x32_bf16 v[72:75], v[168:171], v[216:219], v[72:75]
	v_mfma_f32_16x16x32_bf16 v[72:75], v[172:175], v[220:223], v[72:75]
	v_mfma_f32_16x16x32_bf16 v[76:79], v[160:163], v[216:219], v[76:79]
	v_mfma_f32_16x16x32_bf16 v[76:79], v[164:167], v[220:223], v[76:79]
	s_setprio 0
	s_setprio 1
	v_mfma_f32_16x16x32_bf16 v[116:119], v[176:179], v[192:195], v[116:119]
	v_mfma_f32_16x16x32_bf16 v[116:119], v[180:183], v[196:199], v[116:119]
	v_mfma_f32_16x16x32_bf16 v[112:115], v[184:187], v[192:195], v[112:115]
	v_mfma_f32_16x16x32_bf16 v[112:115], v[188:191], v[196:199], v[112:115]
	v_mfma_f32_16x16x32_bf16 v[96:99], v[184:187], v[200:203], v[96:99]
	v_mfma_f32_16x16x32_bf16 v[96:99], v[188:191], v[204:207], v[96:99]
	v_mfma_f32_16x16x32_bf16 v[100:103], v[176:179], v[200:203], v[100:103]
	v_mfma_f32_16x16x32_bf16 v[100:103], v[180:183], v[204:207], v[100:103]
	v_mfma_f32_16x16x32_bf16 v[84:87], v[176:179], v[208:211], v[84:87]
	v_mfma_f32_16x16x32_bf16 v[84:87], v[180:183], v[212:215], v[84:87]
	v_mfma_f32_16x16x32_bf16 v[80:83], v[184:187], v[208:211], v[80:83]
	v_mfma_f32_16x16x32_bf16 v[80:83], v[188:191], v[212:215], v[80:83]
	v_mfma_f32_16x16x32_bf16 v[64:67], v[184:187], v[216:219], v[64:67]
	v_mfma_f32_16x16x32_bf16 v[64:67], v[188:191], v[220:223], v[64:67]
	v_mfma_f32_16x16x32_bf16 v[68:71], v[176:179], v[216:219], v[68:71]
	v_mfma_f32_16x16x32_bf16 v[68:71], v[180:183], v[220:223], v[68:71]
	s_setprio 0
	s_barrier
; #define PG8_STAGE(bufoff, gbase, voff) do { _Pragma("unroll") for (int _i = 0; _i < 2; ++_i) \
;         __builtin_amdgcn_global_load_lds((const unsigned*)((const char*)(gbase) + (voff)[_i]), (PG8_LAS unsigned*)(lds + (bufoff) + ldsw + _i * 8192), 16, 0, 0); } while (0)
; #define PG8_LDA(dst, b, h) do { _Pragma("unroll") for (int m = 0; m < 4; ++m) _Pragma("unroll") for (int k = 0; k < 2; ++k) dst[m][k] = *(const PG8_LAS bf16x8*)(lds + PG8_SA(b, h) + aoff + m * 2048 + k * 1024); } while (0)
; #define PG8_MMA(ai, bj, At, Bt) do { __builtin_amdgcn_s_setprio(1); _Pragma("unroll") for (int m = 0; m < 4; ++m) _Pragma("unroll") for (int n = 0; n < 2; ++n) _Pragma("unroll") for (int k = 0; k < 2; ++k) \
;         acc[ai][bj][m][n] = __builtin_amdgcn_mfma_f32_16x16x32_bf16(Bt[n][k], At[m][k], acc[ai][bj][m][n], 0, 0, 0); __builtin_amdgcn_s_setprio(0); } while (0)
; #define PG8_WAIT_V(n) asm volatile("s_waitcnt vmcnt(" #n ")" ::: "memory")
; #define PG8_WAIT_L(n) asm volatile("s_waitcnt lgkmcnt(" #n ")" ::: "memory")
; #define PG8_BAR __builtin_amdgcn_s_barrier()
; #define PG8_SCHED __builtin_amdgcn_sched_barrier(0)
; template <class Epi, class Sched, bool ALIGN_EPI = false, bool SP2 = false>
; __device__ __forceinline__ void gemm_phase(PG8_LAS unsigned char* lds, const Gemm g, const Sched& S, const Epi& E) {
;     ...
;             PG8_LDA(At, 1, 1); PG8_STAGE(PG8_SB(1, 0), b3, voffB); PG8_STAGE(PG8_SB(1, 1), b3 + hstep, voffB); PG8_STAGE(PG8_SA(1, 0), a3, voffA);
;             PG8_WAIT_V(8); PG8_WAIT_L(0); PG8_BAR; PG8_MMA(1, 0, At, B0); PG8_MMA(1, 1, At, B1); PG8_BAR; PG8_SCHED;
;     ...
;         if constexpr (ALIGN_EPI) { if (wr == 0) PG8_BAR; }
	s_add_i32 s62, s62, s35
	v_lshl_add_u64 v[224:225], v[224:225], 0, s[18:19]
	s_mov_b32 m0, s62
	ds_read_b128 v[192:195], v159 offset:49152
	ds_read_b128 v[196:199], v159 offset:50176
	ds_read_b128 v[200:203], v159 offset:51200
	ds_read_b128 v[204:207], v159 offset:52224
	ds_read_b128 v[208:211], v159 offset:53248
	ds_read_b128 v[212:215], v159 offset:54272
	ds_read_b128 v[216:219], v159 offset:55296
	ds_read_b128 v[220:223], v159 offset:56320
	global_load_lds_dwordx4 v[224:225], off
	s_add_i32 m0, s62, 0x2000
	s_add_u32 s76, s76, 0x80080
	v_lshl_add_u64 v[224:225], v[226:227], 0, s[18:19]
	s_addc_u32 s77, s77, 0
	s_add_i32 s62, s63, s35
	global_load_lds_dwordx4 v[224:225], off
	v_lshl_add_u64 v[224:225], s[76:77], 0, v[130:131]
	s_mov_b32 m0, s62
	s_nop 0
	global_load_lds_dwordx4 v[224:225], off
	v_lshl_add_u64 v[224:225], s[76:77], 0, v[134:135]
	s_add_i32 m0, s62, 0x2000
	s_nop 0
	global_load_lds_dwordx4 v[224:225], off
	v_lshl_add_u64 v[224:225], v[228:229], 0, s[18:19]
	s_mov_b32 m0, s81
	s_nop 0
	global_load_lds_dwordx4 v[224:225], off
	v_lshl_add_u64 v[224:225], v[230:231], 0, s[18:19]
	s_mov_b32 m0, s82
	s_nop 0
	global_load_lds_dwordx4 v[224:225], off
	s_waitcnt vmcnt(8)
	s_waitcnt lgkmcnt(0)
	s_barrier
	s_setprio 1
	s_waitcnt lgkmcnt(0)
	v_mfma_f32_16x16x32_bf16 v[60:63], v[160:163], v[192:195], v[60:63]
	v_mfma_f32_16x16x32_bf16 v[60:63], v[164:167], v[196:199], v[60:63]
	v_mfma_f32_16x16x32_bf16 v[56:59], v[168:171], v[192:195], v[56:59]
	v_mfma_f32_16x16x32_bf16 v[56:59], v[172:175], v[196:199], v[56:59]
	v_mfma_f32_16x16x32_bf16 v[40:43], v[168:171], v[200:203], v[40:43]
	v_mfma_f32_16x16x32_bf16 v[40:43], v[172:175], v[204:207], v[40:43]
	v_mfma_f32_16x16x32_bf16 v[44:47], v[160:163], v[200:203], v[44:47]
	v_mfma_f32_16x16x32_bf16 v[44:47], v[164:167], v[204:207], v[44:47]
	v_mfma_f32_16x16x32_bf16 v[28:31], v[160:163], v[208:211], v[28:31]
	v_mfma_f32_16x16x32_bf16 v[28:31], v[164:167], v[212:215], v[28:31]
	v_mfma_f32_16x16x32_bf16 v[24:27], v[168:171], v[208:211], v[24:27]
	v_mfma_f32_16x16x32_bf16 v[24:27], v[172:175], v[212:215], v[24:27]
	v_mfma_f32_16x16x32_bf16 v[8:11], v[168:171], v[216:219], v[8:11]
	v_mfma_f32_16x16x32_bf16 v[8:11], v[172:175], v[220:223], v[8:11]
	v_mfma_f32_16x16x32_bf16 v[12:15], v[160:163], v[216:219], v[12:15]
	v_mfma_f32_16x16x32_bf16 v[12:15], v[164:167], v[220:223], v[12:15]
	s_setprio 0
	s_setprio 1
	v_mfma_f32_16x16x32_bf16 v[52:55], v[176:179], v[192:195], v[52:55]
	v_mfma_f32_16x16x32_bf16 v[52:55], v[180:183], v[196:199], v[52:55]
	v_mfma_f32_16x16x32_bf16 v[48:51], v[184:187], v[192:195], v[48:51]
	v_mfma_f32_16x16x32_bf16 v[48:51], v[188:191], v[196:199], v[48:51]
	v_mfma_f32_16x16x32_bf16 v[32:35], v[184:187], v[200:203], v[32:35]
	v_mfma_f32_16x16x32_bf16 v[32:35], v[188:191], v[204:207], v[32:35]
	v_mfma_f32_16x16x32_bf16 v[36:39], v[176:179], v[200:203], v[36:39]
	v_mfma_f32_16x16x32_bf16 v[36:39], v[180:183], v[204:207], v[36:39]
	v_mfma_f32_16x16x32_bf16 v[20:23], v[176:179], v[208:211], v[20:23]
	v_mfma_f32_16x16x32_bf16 v[20:23], v[180:183], v[212:215], v[20:23]
	v_mfma_f32_16x16x32_bf16 v[16:19], v[184:187], v[208:211], v[16:19]
	v_mfma_f32_16x16x32_bf16 v[16:19], v[188:191], v[212:215], v[16:19]
	v_mfma_f32_16x16x32_bf16 v[0:3], v[184:187], v[216:219], v[0:3]
	v_mfma_f32_16x16x32_bf16 v[0:3], v[188:191], v[220:223], v[0:3]
	v_mfma_f32_16x16x32_bf16 v[4:7], v[176:179], v[216:219], v[4:7]
	v_mfma_f32_16x16x32_bf16 v[4:7], v[180:183], v[220:223], v[4:7]
	s_setprio 0
	s_barrier
	s_add_i32 s90, s90, 2
	s_add_u32 s74, s74, 0x100
	s_addc_u32 s75, s75, 0
	s_add_u32 s88, s88, 0x100
	s_addc_u32 s89, s89, 0
	s_cmp_gt_u32 s90, 29
	s_cbranch_scc0 .LBB0_102
	s_and_b64 vcc, exec, s[22:23]
	s_cbranch_vccz .LBB0_105
	s_barrier

; #define PG8_STAGE(bufoff, gbase, voff) do { _Pragma("unroll") for (int _i = 0; _i < 2; ++_i) \
;         __builtin_amdgcn_global_load_lds((const unsigned*)((const char*)(gbase) + (voff)[_i]), (PG8_LAS unsigned*)(lds + (bufoff) + ldsw + _i * 8192), 16, 0, 0); } while (0)
; #define PG8_LDA(dst, b, h) do { _Pragma("unroll") for (int m = 0; m < 4; ++m) _Pragma("unroll") for (int k = 0; k < 2; ++k) dst[m][k] = *(const PG8_LAS bf16x8*)(lds + PG8_SA(b, h) + aoff + m * 2048 + k * 1024); } while (0)
; #define PG8_LDB(dst, b, h) do { _Pragma("unroll") for (int n = 0; n < 2; ++n) _Pragma("unroll") for (int k = 0; k < 2; ++k) dst[n][k] = *(const PG8_LAS bf16x8*)(lds + PG8_SB(b, h) + boff + n * 2048 + k * 1024); } while (0)
; #define PG8_MMA(ai, bj, At, Bt) do { __builtin_amdgcn_s_setprio(1); _Pragma("unroll") for (int m = 0; m < 4; ++m) _Pragma("unroll") for (int n = 0; n < 2; ++n) _Pragma("unroll") for (int k = 0; k < 2; ++k) \
;         acc[ai][bj][m][n] = __builtin_amdgcn_mfma_f32_16x16x32_bf16(Bt[n][k], At[m][k], acc[ai][bj][m][n], 0, 0, 0); __builtin_amdgcn_s_setprio(0); } while (0)
; #define PG8_WAIT_V(n) asm volatile("s_waitcnt vmcnt(" #n ")" ::: "memory")
; #define PG8_WAIT_L(n) asm volatile("s_waitcnt lgkmcnt(" #n ")" ::: "memory")
; template <class Epi, class Sched, bool ALIGN_EPI = false, bool SP2 = false>
; __device__ __forceinline__ void gemm_phase(PG8_LAS unsigned char* lds, const Gemm g, const Sched& S, const Epi& E) {
;     ...
;             const bool last = (t == nt - 2);
;             const char* a1 = cA + (size_t)(t + 1) * kstep;
;             const char* a2 = last ? nA : cA + (size_t)(t + 2) * kstep; const char* b2 = last ? nB : cB + (size_t)(t + 2) * kstep;
;             const char* a3 = a2 + kstep; const char* b3 = b2 + kstep;
;             if (last && has_next) S.a_ready(nxt);
;             if constexpr (SP2) {
;             PG8_LDB(B0, 0, 0); PG8_LDB(B1, 0, 1); PG8_SCHED; PG8_LDA(At, 0, 0); PG8_STAGE(PG8_SA(1, 1), a1 + hstep, voffA);
;             PG8_WAIT_V(8); PG8_WAIT_L(0); PG8_BAR; PG8_MMA(0, 0, At, B0); PG8_MMA(0, 1, At, B1); PG8_BAR; PG8_SCHED;
;             PG8_LDA(At, 0, 1); PG8_STAGE(PG8_SB(0, 0), b2, voffB); PG8_STAGE(PG8_SB(0, 1), b2 + hstep, voffB); PG8_STAGE(PG8_SA(0, 0), a2, voffA);
;             PG8_WAIT_V(8); PG8_WAIT_L(0); PG8_BAR; PG8_MMA(1, 0, At, B0); PG8_MMA(1, 1, At, B1); PG8_BAR; PG8_SCHED;
.LBB0_179:
	ds_read_b128 v[144:147], v155
	ds_read_b128 v[160:163], v155 offset:1024
	ds_read_b128 v[164:167], v155 offset:2048
	ds_read_b128 v[168:171], v155 offset:3072
	ds_read_b128 v[172:175], v156
	ds_read_b128 v[176:179], v156 offset:1024
	ds_read_b128 v[180:183], v156 offset:2048
	ds_read_b128 v[184:187], v156 offset:3072
	s_add_u32 s62, s76, 0xffea0080
	s_addc_u32 s63, s77, -1
	s_cmpk_eq_i32 s92, 0x54
	s_cselect_b32 s81, s7, s63
	s_cselect_b32 s80, s6, s62
	s_cselect_b32 s79, s75, s91
	s_cselect_b32 s78, s74, s50
	v_lshl_add_u64 v[220:221], s[76:77], 0, v[136:137]
	s_add_i32 m0, s52, 0xc000
	ds_read_b128 v[188:191], v157
	ds_read_b128 v[192:195], v157 offset:1024
	ds_read_b128 v[196:199], v157 offset:2048
	ds_read_b128 v[200:203], v157 offset:3072
	ds_read_b128 v[204:207], v157 offset:4096
	ds_read_b128 v[208:211], v157 offset:5120
	ds_read_b128 v[212:215], v157 offset:6144
	ds_read_b128 v[216:219], v157 offset:7168
	global_load_lds_dwordx4 v[220:221], off
	v_lshl_add_u64 v[220:221], s[76:77], 0, v[138:139]
	s_add_i32 m0, s52, 0xe000
	s_nop 0
	global_load_lds_dwordx4 v[220:221], off
	s_waitcnt vmcnt(8)
	s_waitcnt lgkmcnt(0)
	s_barrier
	s_setprio 1
	s_waitcnt lgkmcnt(0)
	v_mfma_f32_16x16x32_bf16 v[124:127], v[144:147], v[188:191], v[124:127]
	v_mfma_f32_16x16x32_bf16 v[124:127], v[160:163], v[192:195], v[124:127]
	v_mfma_f32_16x16x32_bf16 v[120:123], v[164:167], v[188:191], v[120:123]
	v_mfma_f32_16x16x32_bf16 v[120:123], v[168:171], v[192:195], v[120:123]
	v_mfma_f32_16x16x32_bf16 v[104:107], v[164:167], v[196:199], v[104:107]
	v_mfma_f32_16x16x32_bf16 v[104:107], v[168:171], v[200:203], v[104:107]
	v_mfma_f32_16x16x32_bf16 v[108:111], v[144:147], v[196:199], v[108:111]
	v_mfma_f32_16x16x32_bf16 v[108:111], v[160:163], v[200:203], v[108:111]
	v_mfma_f32_16x16x32_bf16 v[92:95], v[144:147], v[204:207], v[92:95]
	v_mfma_f32_16x16x32_bf16 v[92:95], v[160:163], v[208:211], v[92:95]
	v_mfma_f32_16x16x32_bf16 v[88:91], v[164:167], v[204:207], v[88:91]
	v_mfma_f32_16x16x32_bf16 v[88:91], v[168:171], v[208:211], v[88:91]
	v_mfma_f32_16x16x32_bf16 v[72:75], v[164:167], v[212:215], v[72:75]
	v_mfma_f32_16x16x32_bf16 v[72:75], v[168:171], v[216:219], v[72:75]
	v_mfma_f32_16x16x32_bf16 v[76:79], v[144:147], v[212:215], v[76:79]
	v_mfma_f32_16x16x32_bf16 v[76:79], v[160:163], v[216:219], v[76:79]
	s_setprio 0
	s_setprio 1
	v_mfma_f32_16x16x32_bf16 v[116:119], v[172:175], v[188:191], v[116:119]
	v_mfma_f32_16x16x32_bf16 v[116:119], v[176:179], v[192:195], v[116:119]
	v_mfma_f32_16x16x32_bf16 v[112:115], v[180:183], v[188:191], v[112:115]
	v_mfma_f32_16x16x32_bf16 v[112:115], v[184:187], v[192:195], v[112:115]
	v_mfma_f32_16x16x32_bf16 v[96:99], v[180:183], v[196:199], v[96:99]
	v_mfma_f32_16x16x32_bf16 v[96:99], v[184:187], v[200:203], v[96:99]
	v_mfma_f32_16x16x32_bf16 v[100:103], v[172:175], v[196:199], v[100:103]
	v_mfma_f32_16x16x32_bf16 v[100:103], v[176:179], v[200:203], v[100:103]
	v_mfma_f32_16x16x32_bf16 v[84:87], v[172:175], v[204:207], v[84:87]
	v_mfma_f32_16x16x32_bf16 v[84:87], v[176:179], v[208:211], v[84:87]
	v_mfma_f32_16x16x32_bf16 v[80:83], v[180:183], v[204:207], v[80:83]
	v_mfma_f32_16x16x32_bf16 v[80:83], v[184:187], v[208:211], v[80:83]
	v_mfma_f32_16x16x32_bf16 v[64:67], v[180:183], v[212:215], v[64:67]
	v_mfma_f32_16x16x32_bf16 v[64:67], v[184:187], v[216:219], v[64:67]
	v_mfma_f32_16x16x32_bf16 v[68:71], v[172:175], v[212:215], v[68:71]
	v_mfma_f32_16x16x32_bf16 v[68:71], v[176:179], v[216:219], v[68:71]
	s_setprio 0
	s_barrier
	s_add_i32 s62, s86, s35
	v_lshl_add_u64 v[220:221], s[78:79], 0, v[130:131]
	s_mov_b32 m0, s62
	ds_read_b128 v[188:191], v157 offset:16384
	ds_read_b128 v[192:195], v157 offset:17408
	ds_read_b128 v[196:199], v157 offset:18432
	ds_read_b128 v[200:203], v157 offset:19456
	ds_read_b128 v[204:207], v157 offset:20480
	ds_read_b128 v[208:211], v157 offset:21504
	ds_read_b128 v[212:215], v157 offset:22528
	ds_read_b128 v[216:219], v157 offset:23552
	global_load_lds_dwordx4 v[220:221], off
	s_add_i32 m0, s62, 0x2000
	s_add_u32 s94, s78, 0x160000
	v_lshl_add_u64 v[222:223], s[78:79], 0, v[134:135]
	s_addc_u32 s95, s79, 0
	s_add_i32 s62, s87, s35
	global_load_lds_dwordx4 v[222:223], off
	v_lshl_add_u64 v[224:225], s[94:95], 0, v[130:131]
	s_mov_b32 m0, s62
	v_lshl_add_u64 v[226:227], s[80:81], 0, v[132:133]
	global_load_lds_dwordx4 v[224:225], off
	v_lshl_add_u64 v[224:225], s[94:95], 0, v[134:135]
	s_add_i32 m0, s62, 0x2000
	s_nop 0
	global_load_lds_dwordx4 v[224:225], off
	v_lshl_add_u64 v[224:225], s[80:81], 0, v[128:129]
	s_mov_b32 m0, s52
	s_nop 0
	global_load_lds_dwordx4 v[224:225], off
	s_mov_b32 m0, s53
	s_nop 0
	global_load_lds_dwordx4 v[226:227], off
	s_waitcnt vmcnt(8)
	s_waitcnt lgkmcnt(0)
	s_barrier
; #define PG8_STAGE(bufoff, gbase, voff) do { _Pragma("unroll") for (int _i = 0; _i < 2; ++_i) \
;         __builtin_amdgcn_global_load_lds((const unsigned*)((const char*)(gbase) + (voff)[_i]), (PG8_LAS unsigned*)(lds + (bufoff) + ldsw + _i * 8192), 16, 0, 0); } while (0)
; #define PG8_LDA(dst, b, h) do { _Pragma("unroll") for (int m = 0; m < 4; ++m) _Pragma("unroll") for (int k = 0; k < 2; ++k) dst[m][k] = *(const PG8_LAS bf16x8*)(lds + PG8_SA(b, h) + aoff + m * 2048 + k * 1024); } while (0)
; #define PG8_LDB(dst, b, h) do { _Pragma("unroll") for (int n = 0; n < 2; ++n) _Pragma("unroll") for (int k = 0; k < 2; ++k) dst[n][k] = *(const PG8_LAS bf16x8*)(lds + PG8_SB(b, h) + boff + n * 2048 + k * 1024); } while (0)
; #define PG8_MMA(ai, bj, At, Bt) do { __builtin_amdgcn_s_setprio(1); _Pragma("unroll") for (int m = 0; m < 4; ++m) _Pragma("unroll") for (int n = 0; n < 2; ++n) _Pragma("unroll") for (int k = 0; k < 2; ++k) \
;         acc[ai][bj][m][n] = __builtin_amdgcn_mfma_f32_16x16x32_bf16(Bt[n][k], At[m][k], acc[ai][bj][m][n], 0, 0, 0); __builtin_amdgcn_s_setprio(0); } while (0)
; #define PG8_WAIT_V(n) asm volatile("s_waitcnt vmcnt(" #n ")" ::: "memory")
; #define PG8_WAIT_L(n) asm volatile("s_waitcnt lgkmcnt(" #n ")" ::: "memory")
; #define PG8_BAR __builtin_amdgcn_s_barrier()
; #define PG8_SCHED __builtin_amdgcn_sched_barrier(0)
; template <class Epi, class Sched, bool ALIGN_EPI = false, bool SP2 = false>
; __device__ __forceinline__ void gemm_phase(PG8_LAS unsigned char* lds, const Gemm g, const Sched& S, const Epi& E) {
;     ...
;             PG8_WAIT_V(8); PG8_WAIT_L(0); PG8_BAR; PG8_MMA(1, 0, At, B0); PG8_MMA(1, 1, At, B1); PG8_BAR; PG8_SCHED;
;             PG8_LDB(B0, 1, 0); PG8_LDB(B1, 1, 1); PG8_SCHED; PG8_LDA(At, 1, 0); PG8_STAGE(PG8_SA(0, 1), a2 + hstep, voffA);
;             PG8_WAIT_V(8); PG8_WAIT_L(0); PG8_BAR; PG8_MMA(0, 0, At, B0); PG8_MMA(0, 1, At, B1); PG8_BAR; PG8_SCHED;
	s_setprio 1
	s_waitcnt lgkmcnt(0)
	v_mfma_f32_16x16x32_bf16 v[60:63], v[144:147], v[188:191], v[60:63]
	v_mfma_f32_16x16x32_bf16 v[60:63], v[160:163], v[192:195], v[60:63]
	v_mfma_f32_16x16x32_bf16 v[56:59], v[164:167], v[188:191], v[56:59]
	v_mfma_f32_16x16x32_bf16 v[56:59], v[168:171], v[192:195], v[56:59]
	v_mfma_f32_16x16x32_bf16 v[40:43], v[164:167], v[196:199], v[40:43]
	v_mfma_f32_16x16x32_bf16 v[40:43], v[168:171], v[200:203], v[40:43]
	v_mfma_f32_16x16x32_bf16 v[44:47], v[144:147], v[196:199], v[44:47]
	v_mfma_f32_16x16x32_bf16 v[44:47], v[160:163], v[200:203], v[44:47]
	v_mfma_f32_16x16x32_bf16 v[28:31], v[144:147], v[204:207], v[28:31]
	v_mfma_f32_16x16x32_bf16 v[28:31], v[160:163], v[208:211], v[28:31]
	v_mfma_f32_16x16x32_bf16 v[24:27], v[164:167], v[204:207], v[24:27]
	v_mfma_f32_16x16x32_bf16 v[24:27], v[168:171], v[208:211], v[24:27]
	v_mfma_f32_16x16x32_bf16 v[8:11], v[164:167], v[212:215], v[8:11]
	v_mfma_f32_16x16x32_bf16 v[8:11], v[168:171], v[216:219], v[8:11]
	v_mfma_f32_16x16x32_bf16 v[12:15], v[144:147], v[212:215], v[12:15]
	v_mfma_f32_16x16x32_bf16 v[12:15], v[160:163], v[216:219], v[12:15]
	s_setprio 0
	s_setprio 1
	v_mfma_f32_16x16x32_bf16 v[52:55], v[172:175], v[188:191], v[52:55]
	v_mfma_f32_16x16x32_bf16 v[52:55], v[176:179], v[192:195], v[52:55]
	v_mfma_f32_16x16x32_bf16 v[48:51], v[180:183], v[188:191], v[48:51]
	v_mfma_f32_16x16x32_bf16 v[48:51], v[184:187], v[192:195], v[48:51]
	v_mfma_f32_16x16x32_bf16 v[32:35], v[180:183], v[196:199], v[32:35]
	v_mfma_f32_16x16x32_bf16 v[32:35], v[184:187], v[200:203], v[32:35]
	v_mfma_f32_16x16x32_bf16 v[36:39], v[172:175], v[196:199], v[36:39]
	v_mfma_f32_16x16x32_bf16 v[36:39], v[176:179], v[200:203], v[36:39]
	v_mfma_f32_16x16x32_bf16 v[20:23], v[172:175], v[204:207], v[20:23]
	v_mfma_f32_16x16x32_bf16 v[20:23], v[176:179], v[208:211], v[20:23]
	v_mfma_f32_16x16x32_bf16 v[16:19], v[180:183], v[204:207], v[16:19]
	v_mfma_f32_16x16x32_bf16 v[16:19], v[184:187], v[208:211], v[16:19]
	v_mfma_f32_16x16x32_bf16 v[0:3], v[180:183], v[212:215], v[0:3]
	v_mfma_f32_16x16x32_bf16 v[0:3], v[184:187], v[216:219], v[0:3]
	v_mfma_f32_16x16x32_bf16 v[4:7], v[172:175], v[212:215], v[4:7]
	v_mfma_f32_16x16x32_bf16 v[4:7], v[176:179], v[216:219], v[4:7]
	s_setprio 0
	s_barrier
	s_add_i32 s62, 0, 0x18000
	v_add_u32_e32 v159, s62, v153
	s_add_i32 s63, 0, 0x1c000
	ds_read_b128 v[144:147], v159
	ds_read_b128 v[160:163], v159 offset:1024
	ds_read_b128 v[164:167], v159 offset:2048
	ds_read_b128 v[168:171], v159 offset:3072
	v_add_u32_e32 v159, s63, v153
	ds_read_b128 v[172:175], v159
	ds_read_b128 v[176:179], v159 offset:1024
	ds_read_b128 v[180:183], v159 offset:2048
	ds_read_b128 v[184:187], v159 offset:3072
	s_add_u32 s80, s80, 0x160000
	s_addc_u32 s81, s81, 0
	s_mov_b32 m0, s61
	v_lshl_add_u64 v[228:229], s[80:81], 0, v[128:129]
	ds_read_b128 v[188:191], v157 offset:32768
	ds_read_b128 v[192:195], v157 offset:33792
	ds_read_b128 v[196:199], v157 offset:34816
	ds_read_b128 v[200:203], v157 offset:35840
	ds_read_b128 v[204:207], v157 offset:36864
	ds_read_b128 v[208:211], v157 offset:37888
	ds_read_b128 v[212:215], v157 offset:38912
	ds_read_b128 v[216:219], v157 offset:39936
	global_load_lds_dwordx4 v[228:229], off
	v_lshl_add_u64 v[228:229], s[80:81], 0, v[132:133]
	s_mov_b32 m0, s65
	s_nop 0
	global_load_lds_dwordx4 v[228:229], off
	s_waitcnt vmcnt(8)
	s_waitcnt lgkmcnt(0)
	s_barrier
	s_setprio 1
	s_waitcnt lgkmcnt(0)
	v_mfma_f32_16x16x32_bf16 v[124:127], v[144:147], v[188:191], v[124:127]
	v_mfma_f32_16x16x32_bf16 v[124:127], v[160:163], v[192:195], v[124:127]
	v_mfma_f32_16x16x32_bf16 v[120:123], v[164:167], v[188:191], v[120:123]
	v_mfma_f32_16x16x32_bf16 v[120:123], v[168:171], v[192:195], v[120:123]
	v_mfma_f32_16x16x32_bf16 v[104:107], v[164:167], v[196:199], v[104:107]
	v_mfma_f32_16x16x32_bf16 v[104:107], v[168:171], v[200:203], v[104:107]
	v_mfma_f32_16x16x32_bf16 v[108:111], v[144:147], v[196:199], v[108:111]
	v_mfma_f32_16x16x32_bf16 v[108:111], v[160:163], v[200:203], v[108:111]
	v_mfma_f32_16x16x32_bf16 v[92:95], v[144:147], v[204:207], v[92:95]
	v_mfma_f32_16x16x32_bf16 v[92:95], v[160:163], v[208:211], v[92:95]
	v_mfma_f32_16x16x32_bf16 v[88:91], v[164:167], v[204:207], v[88:91]
	v_mfma_f32_16x16x32_bf16 v[88:91], v[168:171], v[208:211], v[88:91]
	v_mfma_f32_16x16x32_bf16 v[72:75], v[164:167], v[212:215], v[72:75]
	v_mfma_f32_16x16x32_bf16 v[72:75], v[168:171], v[216:219], v[72:75]
	v_mfma_f32_16x16x32_bf16 v[76:79], v[144:147], v[212:215], v[76:79]
	v_mfma_f32_16x16x32_bf16 v[76:79], v[160:163], v[216:219], v[76:79]
	s_setprio 0
	s_setprio 1
	v_mfma_f32_16x16x32_bf16 v[116:119], v[172:175], v[188:191], v[116:119]
	v_mfma_f32_16x16x32_bf16 v[116:119], v[176:179], v[192:195], v[116:119]
	v_mfma_f32_16x16x32_bf16 v[112:115], v[180:183], v[188:191], v[112:115]
	v_mfma_f32_16x16x32_bf16 v[112:115], v[184:187], v[192:195], v[112:115]
	v_mfma_f32_16x16x32_bf16 v[96:99], v[180:183], v[196:199], v[96:99]
	v_mfma_f32_16x16x32_bf16 v[96:99], v[184:187], v[200:203], v[96:99]
	v_mfma_f32_16x16x32_bf16 v[100:103], v[172:175], v[196:199], v[100:103]
	v_mfma_f32_16x16x32_bf16 v[100:103], v[176:179], v[200:203], v[100:103]
	v_mfma_f32_16x16x32_bf16 v[84:87], v[172:175], v[204:207], v[84:87]
	v_mfma_f32_16x16x32_bf16 v[84:87], v[176:179], v[208:211], v[84:87]
	v_mfma_f32_16x16x32_bf16 v[80:83], v[180:183], v[204:207], v[80:83]
	v_mfma_f32_16x16x32_bf16 v[80:83], v[184:187], v[208:211], v[80:83]
	v_mfma_f32_16x16x32_bf16 v[64:67], v[180:183], v[212:215], v[64:67]
	v_mfma_f32_16x16x32_bf16 v[64:67], v[184:187], v[216:219], v[64:67]
	v_mfma_f32_16x16x32_bf16 v[68:71], v[172:175], v[212:215], v[68:71]
	v_mfma_f32_16x16x32_bf16 v[68:71], v[176:179], v[216:219], v[68:71]
	s_setprio 0
	s_barrier
; #define PG8_STAGE(bufoff, gbase, voff) do { _Pragma("unroll") for (int _i = 0; _i < 2; ++_i) \
;         __builtin_amdgcn_global_load_lds((const unsigned*)((const char*)(gbase) + (voff)[_i]), (PG8_LAS unsigned*)(lds + (bufoff) + ldsw + _i * 8192), 16, 0, 0); } while (0)
; #define PG8_LDA(dst, b, h) do { _Pragma("unroll") for (int m = 0; m < 4; ++m) _Pragma("unroll") for (int k = 0; k < 2; ++k) dst[m][k] = *(const PG8_LAS bf16x8*)(lds + PG8_SA(b, h) + aoff + m * 2048 + k * 1024); } while (0)
; #define PG8_MMA(ai, bj, At, Bt) do { __builtin_amdgcn_s_setprio(1); _Pragma("unroll") for (int m = 0; m < 4; ++m) _Pragma("unroll") for (int n = 0; n < 2; ++n) _Pragma("unroll") for (int k = 0; k < 2; ++k) \
;         acc[ai][bj][m][n] = __builtin_amdgcn_mfma_f32_16x16x32_bf16(Bt[n][k], At[m][k], acc[ai][bj][m][n], 0, 0, 0); __builtin_amdgcn_s_setprio(0); } while (0)
; #define PG8_WAIT_V(n) asm volatile("s_waitcnt vmcnt(" #n ")" ::: "memory")
; #define PG8_WAIT_L(n) asm volatile("s_waitcnt lgkmcnt(" #n ")" ::: "memory")
; #define PG8_BAR __builtin_amdgcn_s_barrier()
; #define PG8_SCHED __builtin_amdgcn_sched_barrier(0)
; template <class Epi, class Sched, bool ALIGN_EPI = false, bool SP2 = false>
; __device__ __forceinline__ void gemm_phase(PG8_LAS unsigned char* lds, const Gemm g, const Sched& S, const Epi& E) {
;     ...
;             PG8_LDA(At, 1, 1); PG8_STAGE(PG8_SB(1, 0), b3, voffB); PG8_STAGE(PG8_SB(1, 1), b3 + hstep, voffB); PG8_STAGE(PG8_SA(1, 0), a3, voffA);
;             PG8_WAIT_V(8); PG8_WAIT_L(0); PG8_BAR; PG8_MMA(1, 0, At, B0); PG8_MMA(1, 1, At, B1); PG8_BAR; PG8_SCHED;
;     ...
;         if constexpr (ALIGN_EPI) { if (wr == 0) PG8_BAR; }
	s_add_i32 s62, s62, s35
	v_lshl_add_u64 v[220:221], v[220:221], 0, s[56:57]
	s_mov_b32 m0, s62
	ds_read_b128 v[188:191], v157 offset:49152
	ds_read_b128 v[192:195], v157 offset:50176
	ds_read_b128 v[196:199], v157 offset:51200
	ds_read_b128 v[200:203], v157 offset:52224
	ds_read_b128 v[204:207], v157 offset:53248
	ds_read_b128 v[208:211], v157 offset:54272
	ds_read_b128 v[212:215], v157 offset:55296
	ds_read_b128 v[216:219], v157 offset:56320
	global_load_lds_dwordx4 v[220:221], off
	s_add_i32 m0, s62, 0x2000
	s_add_u32 s78, s78, 0x160080
	v_lshl_add_u64 v[220:221], v[222:223], 0, s[56:57]
	s_addc_u32 s79, s79, 0
	s_add_i32 s62, s63, s35
	global_load_lds_dwordx4 v[220:221], off
	v_lshl_add_u64 v[220:221], s[78:79], 0, v[130:131]
	s_mov_b32 m0, s62
	s_nop 0
	global_load_lds_dwordx4 v[220:221], off
	v_lshl_add_u64 v[220:221], s[78:79], 0, v[134:135]
	s_add_i32 m0, s62, 0x2000
	s_nop 0
	global_load_lds_dwordx4 v[220:221], off
	v_lshl_add_u64 v[220:221], v[224:225], 0, s[56:57]
	s_mov_b32 m0, s83
	s_nop 0
	global_load_lds_dwordx4 v[220:221], off
	v_lshl_add_u64 v[220:221], v[226:227], 0, s[56:57]
	s_mov_b32 m0, s84
	s_nop 0
	global_load_lds_dwordx4 v[220:221], off
	s_waitcnt vmcnt(8)
	s_waitcnt lgkmcnt(0)
	s_barrier
	s_setprio 1
	s_waitcnt lgkmcnt(0)
	v_mfma_f32_16x16x32_bf16 v[60:63], v[144:147], v[188:191], v[60:63]
	v_mfma_f32_16x16x32_bf16 v[60:63], v[160:163], v[192:195], v[60:63]
	v_mfma_f32_16x16x32_bf16 v[56:59], v[164:167], v[188:191], v[56:59]
	v_mfma_f32_16x16x32_bf16 v[56:59], v[168:171], v[192:195], v[56:59]
	v_mfma_f32_16x16x32_bf16 v[40:43], v[164:167], v[196:199], v[40:43]
	v_mfma_f32_16x16x32_bf16 v[40:43], v[168:171], v[200:203], v[40:43]
	v_mfma_f32_16x16x32_bf16 v[44:47], v[144:147], v[196:199], v[44:47]
	v_mfma_f32_16x16x32_bf16 v[44:47], v[160:163], v[200:203], v[44:47]
	v_mfma_f32_16x16x32_bf16 v[28:31], v[144:147], v[204:207], v[28:31]
	v_mfma_f32_16x16x32_bf16 v[28:31], v[160:163], v[208:211], v[28:31]
	v_mfma_f32_16x16x32_bf16 v[24:27], v[164:167], v[204:207], v[24:27]
	v_mfma_f32_16x16x32_bf16 v[24:27], v[168:171], v[208:211], v[24:27]
	v_mfma_f32_16x16x32_bf16 v[8:11], v[164:167], v[212:215], v[8:11]
	v_mfma_f32_16x16x32_bf16 v[8:11], v[168:171], v[216:219], v[8:11]
	v_mfma_f32_16x16x32_bf16 v[12:15], v[144:147], v[212:215], v[12:15]
	v_mfma_f32_16x16x32_bf16 v[12:15], v[160:163], v[216:219], v[12:15]
	s_setprio 0
	s_setprio 1
	v_mfma_f32_16x16x32_bf16 v[52:55], v[172:175], v[188:191], v[52:55]
	v_mfma_f32_16x16x32_bf16 v[52:55], v[176:179], v[192:195], v[52:55]
	v_mfma_f32_16x16x32_bf16 v[48:51], v[180:183], v[188:191], v[48:51]
	v_mfma_f32_16x16x32_bf16 v[48:51], v[184:187], v[192:195], v[48:51]
	v_mfma_f32_16x16x32_bf16 v[32:35], v[180:183], v[196:199], v[32:35]
	v_mfma_f32_16x16x32_bf16 v[32:35], v[184:187], v[200:203], v[32:35]
	v_mfma_f32_16x16x32_bf16 v[36:39], v[172:175], v[196:199], v[36:39]
	v_mfma_f32_16x16x32_bf16 v[36:39], v[176:179], v[200:203], v[36:39]
	v_mfma_f32_16x16x32_bf16 v[20:23], v[172:175], v[204:207], v[20:23]
	v_mfma_f32_16x16x32_bf16 v[20:23], v[176:179], v[208:211], v[20:23]
	v_mfma_f32_16x16x32_bf16 v[16:19], v[180:183], v[204:207], v[16:19]
	v_mfma_f32_16x16x32_bf16 v[16:19], v[184:187], v[208:211], v[16:19]
	v_mfma_f32_16x16x32_bf16 v[0:3], v[180:183], v[212:215], v[0:3]
	v_mfma_f32_16x16x32_bf16 v[0:3], v[184:187], v[216:219], v[0:3]
	v_mfma_f32_16x16x32_bf16 v[4:7], v[172:175], v[212:215], v[4:7]
	v_mfma_f32_16x16x32_bf16 v[4:7], v[176:179], v[216:219], v[4:7]
	s_setprio 0
	s_barrier
	s_add_i32 s92, s92, 2
	s_add_u32 s76, s76, 0x100
	s_addc_u32 s77, s77, 0
	s_add_u32 s50, s50, 0x100
	s_addc_u32 s91, s91, 0
	s_cmpk_gt_u32 s92, 0x55
	s_cbranch_scc0 .LBB0_179
	s_and_b64 vcc, exec, s[58:59]
	s_cbranch_vccz .LBB0_182
	s_barrier

; #define PG8_STAGE(bufoff, gbase, voff) do { _Pragma("unroll") for (int _i = 0; _i < 2; ++_i) \
;         __builtin_amdgcn_global_load_lds((const unsigned*)((const char*)(gbase) + (voff)[_i]), (PG8_LAS unsigned*)(lds + (bufoff) + ldsw + _i * 8192), 16, 0, 0); } while (0)
; #define PG8_LDA(dst, b, h) do { _Pragma("unroll") for (int m = 0; m < 4; ++m) _Pragma("unroll") for (int k = 0; k < 2; ++k) dst[m][k] = *(const PG8_LAS bf16x8*)(lds + PG8_SA(b, h) + aoff + m * 2048 + k * 1024); } while (0)
; #define PG8_LDB(dst, b, h) do { _Pragma("unroll") for (int n = 0; n < 2; ++n) _Pragma("unroll") for (int k = 0; k < 2; ++k) dst[n][k] = *(const PG8_LAS bf16x8*)(lds + PG8_SB(b, h) + boff + n * 2048 + k * 1024); } while (0)
; #define PG8_MMA(ai, bj, At, Bt) do { __builtin_amdgcn_s_setprio(1); _Pragma("unroll") for (int m = 0; m < 4; ++m) _Pragma("unroll") for (int n = 0; n < 2; ++n) _Pragma("unroll") for (int k = 0; k < 2; ++k) \
;         acc[ai][bj][m][n] = __builtin_amdgcn_mfma_f32_16x16x32_bf16(Bt[n][k], At[m][k], acc[ai][bj][m][n], 0, 0, 0); __builtin_amdgcn_s_setprio(0); } while (0)
; #define PG8_WAIT_V(n) asm volatile("s_waitcnt vmcnt(" #n ")" ::: "memory")
; #define PG8_WAIT_L(n) asm volatile("s_waitcnt lgkmcnt(" #n ")" ::: "memory")
; template <class Epi, class Sched, bool ALIGN_EPI = false, bool SP2 = false>
; __device__ __forceinline__ void gemm_phase(PG8_LAS unsigned char* lds, const Gemm g, const Sched& S, const Epi& E) {
;     ...
;             const bool last = (t == nt - 2);
;             const char* a1 = cA + (size_t)(t + 1) * kstep;
;             const char* a2 = last ? nA : cA + (size_t)(t + 2) * kstep; const char* b2 = last ? nB : cB + (size_t)(t + 2) * kstep;
;             const char* a3 = a2 + kstep; const char* b3 = b2 + kstep;
;             if (last && has_next) S.a_ready(nxt);
;             if constexpr (SP2) {
;             PG8_LDB(B0, 0, 0); PG8_LDB(B1, 0, 1); PG8_SCHED; PG8_LDA(At, 0, 0); PG8_STAGE(PG8_SA(1, 1), a1 + hstep, voffA);
;             PG8_WAIT_V(8); PG8_WAIT_L(0); PG8_BAR; PG8_MMA(0, 0, At, B0); PG8_MMA(0, 1, At, B1); PG8_BAR; PG8_SCHED;
;             PG8_LDA(At, 0, 1); PG8_STAGE(PG8_SB(0, 0), b2, voffB); PG8_STAGE(PG8_SB(0, 1), b2 + hstep, voffB); PG8_STAGE(PG8_SA(0, 0), a2, voffA);
;             PG8_WAIT_V(8); PG8_WAIT_L(0); PG8_BAR; PG8_MMA(1, 0, At, B0); PG8_MMA(1, 1, At, B1); PG8_BAR; PG8_SCHED;
.LBB0_326:
	ds_read_b128 v[178:181], v176
	ds_read_b128 v[182:185], v176 offset:1024
	ds_read_b128 v[186:189], v176 offset:2048
	ds_read_b128 v[190:193], v176 offset:3072
	ds_read_b128 v[194:197], v177
	ds_read_b128 v[198:201], v177 offset:1024
	ds_read_b128 v[202:205], v177 offset:2048
	ds_read_b128 v[206:209], v177 offset:3072
	s_add_u32 s62, s76, 0xfff80080
	s_addc_u32 s63, s77, -1
	s_cmp_eq_u32 s75, 28
	s_cselect_b32 s81, s10, s63
	s_cselect_b32 s80, s11, s62
	s_cselect_b32 s79, s51, s67
	s_cselect_b32 s78, s55, s57
	v_lshl_add_u64 v[166:167], s[76:77], 0, v[146:147]
	s_add_i32 m0, s64, 0xc000
	ds_read_b128 v[210:213], v145
	ds_read_b128 v[214:217], v145 offset:1024
	ds_read_b128 v[218:221], v145 offset:2048
	ds_read_b128 v[222:225], v145 offset:3072
	ds_read_b128 v[226:229], v145 offset:4096
	ds_read_b128 v[230:233], v145 offset:5120
	ds_read_b128 v[234:237], v145 offset:6144
	ds_read_b128 v[238:241], v145 offset:7168
	global_load_lds_dwordx4 v[166:167], off
	v_lshl_add_u64 v[166:167], s[76:77], 0, v[152:153]
	s_add_i32 m0, s64, 0xe000
	s_nop 0
	global_load_lds_dwordx4 v[166:167], off
	s_waitcnt vmcnt(8)
	s_waitcnt lgkmcnt(0)
	s_barrier
	s_setprio 1
	s_waitcnt lgkmcnt(0)
	v_mfma_f32_16x16x32_bf16 v[124:127], v[178:181], v[210:213], v[124:127]
	v_mfma_f32_16x16x32_bf16 v[124:127], v[182:185], v[214:217], v[124:127]
	v_mfma_f32_16x16x32_bf16 v[120:123], v[186:189], v[210:213], v[120:123]
	v_mfma_f32_16x16x32_bf16 v[120:123], v[190:193], v[214:217], v[120:123]
	v_mfma_f32_16x16x32_bf16 v[112:115], v[186:189], v[218:221], v[112:115]
	v_mfma_f32_16x16x32_bf16 v[112:115], v[190:193], v[222:225], v[112:115]
	v_mfma_f32_16x16x32_bf16 v[116:119], v[178:181], v[218:221], v[116:119]
	v_mfma_f32_16x16x32_bf16 v[116:119], v[182:185], v[222:225], v[116:119]
	v_mfma_f32_16x16x32_bf16 v[108:111], v[178:181], v[226:229], v[108:111]
	v_mfma_f32_16x16x32_bf16 v[108:111], v[182:185], v[230:233], v[108:111]
	v_mfma_f32_16x16x32_bf16 v[104:107], v[186:189], v[226:229], v[104:107]
	v_mfma_f32_16x16x32_bf16 v[104:107], v[190:193], v[230:233], v[104:107]
	v_mfma_f32_16x16x32_bf16 v[96:99], v[186:189], v[234:237], v[96:99]
	v_mfma_f32_16x16x32_bf16 v[96:99], v[190:193], v[238:241], v[96:99]
	v_mfma_f32_16x16x32_bf16 v[100:103], v[178:181], v[234:237], v[100:103]
	v_mfma_f32_16x16x32_bf16 v[100:103], v[182:185], v[238:241], v[100:103]
	s_setprio 0
	s_setprio 1
	v_mfma_f32_16x16x32_bf16 v[68:71], v[194:197], v[210:213], v[68:71]
	v_mfma_f32_16x16x32_bf16 v[68:71], v[198:201], v[214:217], v[68:71]
	v_mfma_f32_16x16x32_bf16 v[64:67], v[202:205], v[210:213], v[64:67]
	v_mfma_f32_16x16x32_bf16 v[64:67], v[206:209], v[214:217], v[64:67]
	v_mfma_f32_16x16x32_bf16 v[48:51], v[202:205], v[218:221], v[48:51]
	v_mfma_f32_16x16x32_bf16 v[48:51], v[206:209], v[222:225], v[48:51]
	v_mfma_f32_16x16x32_bf16 v[52:55], v[194:197], v[218:221], v[52:55]
	v_mfma_f32_16x16x32_bf16 v[52:55], v[198:201], v[222:225], v[52:55]
	v_mfma_f32_16x16x32_bf16 v[44:47], v[194:197], v[226:229], v[44:47]
	v_mfma_f32_16x16x32_bf16 v[44:47], v[198:201], v[230:233], v[44:47]
	v_mfma_f32_16x16x32_bf16 v[40:43], v[202:205], v[226:229], v[40:43]
	v_mfma_f32_16x16x32_bf16 v[40:43], v[206:209], v[230:233], v[40:43]
	v_mfma_f32_16x16x32_bf16 v[32:35], v[202:205], v[234:237], v[32:35]
	v_mfma_f32_16x16x32_bf16 v[32:35], v[206:209], v[238:241], v[32:35]
	v_mfma_f32_16x16x32_bf16 v[36:39], v[194:197], v[234:237], v[36:39]
	v_mfma_f32_16x16x32_bf16 v[36:39], v[198:201], v[238:241], v[36:39]
	s_setprio 0
	s_barrier
	s_add_i32 s62, s53, s3
	v_lshl_add_u64 v[166:167], s[78:79], 0, v[130:131]
	s_mov_b32 m0, s62
	ds_read_b128 v[210:213], v145 offset:16384
	ds_read_b128 v[214:217], v145 offset:17408
	ds_read_b128 v[218:221], v145 offset:18432
	ds_read_b128 v[222:225], v145 offset:19456
	ds_read_b128 v[226:229], v145 offset:20480
	ds_read_b128 v[230:233], v145 offset:21504
	ds_read_b128 v[234:237], v145 offset:22528
	ds_read_b128 v[238:241], v145 offset:23552
	global_load_lds_dwordx4 v[166:167], off
	s_add_i32 m0, s62, 0x2000
	s_add_u32 s82, s78, 0x80000
	v_lshl_add_u64 v[242:243], s[78:79], 0, v[134:135]
	s_addc_u32 s83, s79, 0
	s_add_i32 s62, s66, s3
	global_load_lds_dwordx4 v[242:243], off
	v_lshl_add_u64 v[244:245], s[82:83], 0, v[130:131]
	s_mov_b32 m0, s62
	v_lshl_add_u64 v[246:247], s[80:81], 0, v[132:133]
	global_load_lds_dwordx4 v[244:245], off
	v_lshl_add_u64 v[244:245], s[82:83], 0, v[134:135]
	s_add_i32 m0, s62, 0x2000
	s_nop 0
	global_load_lds_dwordx4 v[244:245], off
	v_lshl_add_u64 v[244:245], s[80:81], 0, v[128:129]
	s_mov_b32 m0, s64
	s_nop 0
	global_load_lds_dwordx4 v[244:245], off
	s_mov_b32 m0, s65
	s_nop 0
	global_load_lds_dwordx4 v[246:247], off
	s_waitcnt vmcnt(8)
	s_waitcnt lgkmcnt(0)
	s_barrier
; #define PG8_STAGE(bufoff, gbase, voff) do { _Pragma("unroll") for (int _i = 0; _i < 2; ++_i) \
;         __builtin_amdgcn_global_load_lds((const unsigned*)((const char*)(gbase) + (voff)[_i]), (PG8_LAS unsigned*)(lds + (bufoff) + ldsw + _i * 8192), 16, 0, 0); } while (0)
; #define PG8_LDA(dst, b, h) do { _Pragma("unroll") for (int m = 0; m < 4; ++m) _Pragma("unroll") for (int k = 0; k < 2; ++k) dst[m][k] = *(const PG8_LAS bf16x8*)(lds + PG8_SA(b, h) + aoff + m * 2048 + k * 1024); } while (0)
; #define PG8_LDB(dst, b, h) do { _Pragma("unroll") for (int n = 0; n < 2; ++n) _Pragma("unroll") for (int k = 0; k < 2; ++k) dst[n][k] = *(const PG8_LAS bf16x8*)(lds + PG8_SB(b, h) + boff + n * 2048 + k * 1024); } while (0)
; #define PG8_MMA(ai, bj, At, Bt) do { __builtin_amdgcn_s_setprio(1); _Pragma("unroll") for (int m = 0; m < 4; ++m) _Pragma("unroll") for (int n = 0; n < 2; ++n) _Pragma("unroll") for (int k = 0; k < 2; ++k) \
;         acc[ai][bj][m][n] = __builtin_amdgcn_mfma_f32_16x16x32_bf16(Bt[n][k], At[m][k], acc[ai][bj][m][n], 0, 0, 0); __builtin_amdgcn_s_setprio(0); } while (0)
; #define PG8_WAIT_V(n) asm volatile("s_waitcnt vmcnt(" #n ")" ::: "memory")
; #define PG8_WAIT_L(n) asm volatile("s_waitcnt lgkmcnt(" #n ")" ::: "memory")
; #define PG8_BAR __builtin_amdgcn_s_barrier()
; #define PG8_SCHED __builtin_amdgcn_sched_barrier(0)
; template <class Epi, class Sched, bool ALIGN_EPI = false, bool SP2 = false>
; __device__ __forceinline__ void gemm_phase(PG8_LAS unsigned char* lds, const Gemm g, const Sched& S, const Epi& E) {
;     ...
;             PG8_WAIT_V(8); PG8_WAIT_L(0); PG8_BAR; PG8_MMA(1, 0, At, B0); PG8_MMA(1, 1, At, B1); PG8_BAR; PG8_SCHED;
;             PG8_LDB(B0, 1, 0); PG8_LDB(B1, 1, 1); PG8_SCHED; PG8_LDA(At, 1, 0); PG8_STAGE(PG8_SA(0, 1), a2 + hstep, voffA);
;             PG8_WAIT_V(8); PG8_WAIT_L(0); PG8_BAR; PG8_MMA(0, 0, At, B0); PG8_MMA(0, 1, At, B1); PG8_BAR; PG8_SCHED;
	s_setprio 1
	s_waitcnt lgkmcnt(0)
	v_mfma_f32_16x16x32_bf16 v[92:95], v[178:181], v[210:213], v[92:95]
	v_mfma_f32_16x16x32_bf16 v[92:95], v[182:185], v[214:217], v[92:95]
	v_mfma_f32_16x16x32_bf16 v[88:91], v[186:189], v[210:213], v[88:91]
	v_mfma_f32_16x16x32_bf16 v[88:91], v[190:193], v[214:217], v[88:91]
	v_mfma_f32_16x16x32_bf16 v[80:83], v[186:189], v[218:221], v[80:83]
	v_mfma_f32_16x16x32_bf16 v[80:83], v[190:193], v[222:225], v[80:83]
	v_mfma_f32_16x16x32_bf16 v[84:87], v[178:181], v[218:221], v[84:87]
	v_mfma_f32_16x16x32_bf16 v[84:87], v[182:185], v[222:225], v[84:87]
	v_mfma_f32_16x16x32_bf16 v[76:79], v[178:181], v[226:229], v[76:79]
	v_mfma_f32_16x16x32_bf16 v[76:79], v[182:185], v[230:233], v[76:79]
	v_mfma_f32_16x16x32_bf16 v[72:75], v[186:189], v[226:229], v[72:75]
	v_mfma_f32_16x16x32_bf16 v[72:75], v[190:193], v[230:233], v[72:75]
	v_mfma_f32_16x16x32_bf16 v[56:59], v[186:189], v[234:237], v[56:59]
	v_mfma_f32_16x16x32_bf16 v[56:59], v[190:193], v[238:241], v[56:59]
	v_mfma_f32_16x16x32_bf16 v[60:63], v[178:181], v[234:237], v[60:63]
	v_mfma_f32_16x16x32_bf16 v[60:63], v[182:185], v[238:241], v[60:63]
	s_setprio 0
	s_setprio 1
	v_mfma_f32_16x16x32_bf16 v[28:31], v[194:197], v[210:213], v[28:31]
	v_mfma_f32_16x16x32_bf16 v[28:31], v[198:201], v[214:217], v[28:31]
	v_mfma_f32_16x16x32_bf16 v[24:27], v[202:205], v[210:213], v[24:27]
	v_mfma_f32_16x16x32_bf16 v[24:27], v[206:209], v[214:217], v[24:27]
	v_mfma_f32_16x16x32_bf16 v[16:19], v[202:205], v[218:221], v[16:19]
	v_mfma_f32_16x16x32_bf16 v[16:19], v[206:209], v[222:225], v[16:19]
	v_mfma_f32_16x16x32_bf16 v[20:23], v[194:197], v[218:221], v[20:23]
	v_mfma_f32_16x16x32_bf16 v[20:23], v[198:201], v[222:225], v[20:23]
	v_mfma_f32_16x16x32_bf16 v[12:15], v[194:197], v[226:229], v[12:15]
	v_mfma_f32_16x16x32_bf16 v[12:15], v[198:201], v[230:233], v[12:15]
	v_mfma_f32_16x16x32_bf16 v[8:11], v[202:205], v[226:229], v[8:11]
	v_mfma_f32_16x16x32_bf16 v[8:11], v[206:209], v[230:233], v[8:11]
	v_mfma_f32_16x16x32_bf16 v[0:3], v[202:205], v[234:237], v[0:3]
	v_mfma_f32_16x16x32_bf16 v[0:3], v[206:209], v[238:241], v[0:3]
	v_mfma_f32_16x16x32_bf16 v[4:7], v[194:197], v[234:237], v[4:7]
	v_mfma_f32_16x16x32_bf16 v[4:7], v[198:201], v[238:241], v[4:7]
	s_setprio 0
	s_barrier
	s_add_i32 s62, 0, 0x18000
	s_add_i32 s63, 0, 0x1c000
	v_add_u32_e32 v190, s62, v143
	v_add_u32_e32 v206, s63, v143
	ds_read_b128 v[178:181], v190
	ds_read_b128 v[182:185], v190 offset:1024
	ds_read_b128 v[186:189], v190 offset:2048
	ds_read_b128 v[190:193], v190 offset:3072
	ds_read_b128 v[194:197], v206
	ds_read_b128 v[198:201], v206 offset:1024
	ds_read_b128 v[202:205], v206 offset:2048
	ds_read_b128 v[206:209], v206 offset:3072
	s_add_u32 s80, s80, 0x80000
	s_addc_u32 s81, s81, 0
	s_mov_b32 m0, s86
	v_lshl_add_u64 v[248:249], s[80:81], 0, v[128:129]
	ds_read_b128 v[210:213], v145 offset:32768
	ds_read_b128 v[214:217], v145 offset:33792
	ds_read_b128 v[218:221], v145 offset:34816
	ds_read_b128 v[222:225], v145 offset:35840
	ds_read_b128 v[226:229], v145 offset:36864
	ds_read_b128 v[230:233], v145 offset:37888
	ds_read_b128 v[234:237], v145 offset:38912
	ds_read_b128 v[238:241], v145 offset:39936
	global_load_lds_dwordx4 v[248:249], off
	v_lshl_add_u64 v[248:249], s[80:81], 0, v[132:133]
	s_mov_b32 m0, s87
	s_nop 0
	global_load_lds_dwordx4 v[248:249], off
	s_waitcnt vmcnt(8)
	s_waitcnt lgkmcnt(0)
	s_barrier
	s_setprio 1
	s_waitcnt lgkmcnt(0)
	v_mfma_f32_16x16x32_bf16 v[124:127], v[178:181], v[210:213], v[124:127]
	v_mfma_f32_16x16x32_bf16 v[124:127], v[182:185], v[214:217], v[124:127]
	v_mfma_f32_16x16x32_bf16 v[120:123], v[186:189], v[210:213], v[120:123]
	v_mfma_f32_16x16x32_bf16 v[120:123], v[190:193], v[214:217], v[120:123]
	v_mfma_f32_16x16x32_bf16 v[112:115], v[186:189], v[218:221], v[112:115]
	v_mfma_f32_16x16x32_bf16 v[112:115], v[190:193], v[222:225], v[112:115]
	v_mfma_f32_16x16x32_bf16 v[116:119], v[178:181], v[218:221], v[116:119]
	v_mfma_f32_16x16x32_bf16 v[116:119], v[182:185], v[222:225], v[116:119]
	v_mfma_f32_16x16x32_bf16 v[108:111], v[178:181], v[226:229], v[108:111]
	v_mfma_f32_16x16x32_bf16 v[108:111], v[182:185], v[230:233], v[108:111]
	v_mfma_f32_16x16x32_bf16 v[104:107], v[186:189], v[226:229], v[104:107]
	v_mfma_f32_16x16x32_bf16 v[104:107], v[190:193], v[230:233], v[104:107]
	v_mfma_f32_16x16x32_bf16 v[96:99], v[186:189], v[234:237], v[96:99]
	v_mfma_f32_16x16x32_bf16 v[96:99], v[190:193], v[238:241], v[96:99]
	v_mfma_f32_16x16x32_bf16 v[100:103], v[178:181], v[234:237], v[100:103]
	v_mfma_f32_16x16x32_bf16 v[100:103], v[182:185], v[238:241], v[100:103]
	s_setprio 0
	s_setprio 1
	v_mfma_f32_16x16x32_bf16 v[68:71], v[194:197], v[210:213], v[68:71]
	v_mfma_f32_16x16x32_bf16 v[68:71], v[198:201], v[214:217], v[68:71]
	v_mfma_f32_16x16x32_bf16 v[64:67], v[202:205], v[210:213], v[64:67]
	v_mfma_f32_16x16x32_bf16 v[64:67], v[206:209], v[214:217], v[64:67]
	v_mfma_f32_16x16x32_bf16 v[48:51], v[202:205], v[218:221], v[48:51]
	v_mfma_f32_16x16x32_bf16 v[48:51], v[206:209], v[222:225], v[48:51]
	v_mfma_f32_16x16x32_bf16 v[52:55], v[194:197], v[218:221], v[52:55]
	v_mfma_f32_16x16x32_bf16 v[52:55], v[198:201], v[222:225], v[52:55]
	v_mfma_f32_16x16x32_bf16 v[44:47], v[194:197], v[226:229], v[44:47]
	v_mfma_f32_16x16x32_bf16 v[44:47], v[198:201], v[230:233], v[44:47]
	v_mfma_f32_16x16x32_bf16 v[40:43], v[202:205], v[226:229], v[40:43]
	v_mfma_f32_16x16x32_bf16 v[40:43], v[206:209], v[230:233], v[40:43]
	v_mfma_f32_16x16x32_bf16 v[32:35], v[202:205], v[234:237], v[32:35]
	v_mfma_f32_16x16x32_bf16 v[32:35], v[206:209], v[238:241], v[32:35]
	v_mfma_f32_16x16x32_bf16 v[36:39], v[194:197], v[234:237], v[36:39]
	v_mfma_f32_16x16x32_bf16 v[36:39], v[198:201], v[238:241], v[36:39]
	s_setprio 0
	s_barrier
; #define PG8_STAGE(bufoff, gbase, voff) do { _Pragma("unroll") for (int _i = 0; _i < 2; ++_i) \
;         __builtin_amdgcn_global_load_lds((const unsigned*)((const char*)(gbase) + (voff)[_i]), (PG8_LAS unsigned*)(lds + (bufoff) + ldsw + _i * 8192), 16, 0, 0); } while (0)
; #define PG8_LDA(dst, b, h) do { _Pragma("unroll") for (int m = 0; m < 4; ++m) _Pragma("unroll") for (int k = 0; k < 2; ++k) dst[m][k] = *(const PG8_LAS bf16x8*)(lds + PG8_SA(b, h) + aoff + m * 2048 + k * 1024); } while (0)
; #define PG8_MMA(ai, bj, At, Bt) do { __builtin_amdgcn_s_setprio(1); _Pragma("unroll") for (int m = 0; m < 4; ++m) _Pragma("unroll") for (int n = 0; n < 2; ++n) _Pragma("unroll") for (int k = 0; k < 2; ++k) \
;         acc[ai][bj][m][n] = __builtin_amdgcn_mfma_f32_16x16x32_bf16(Bt[n][k], At[m][k], acc[ai][bj][m][n], 0, 0, 0); __builtin_amdgcn_s_setprio(0); } while (0)
; #define PG8_WAIT_V(n) asm volatile("s_waitcnt vmcnt(" #n ")" ::: "memory")
; #define PG8_WAIT_L(n) asm volatile("s_waitcnt lgkmcnt(" #n ")" ::: "memory")
; #define PG8_BAR __builtin_amdgcn_s_barrier()
; #define PG8_SCHED __builtin_amdgcn_sched_barrier(0)
; template <class Epi, class Sched, bool ALIGN_EPI = false, bool SP2 = false>
; __device__ __forceinline__ void gemm_phase(PG8_LAS unsigned char* lds, const Gemm g, const Sched& S, const Epi& E) {
;     ...
;             PG8_LDA(At, 1, 1); PG8_STAGE(PG8_SB(1, 0), b3, voffB); PG8_STAGE(PG8_SB(1, 1), b3 + hstep, voffB); PG8_STAGE(PG8_SA(1, 0), a3, voffA);
;             PG8_WAIT_V(8); PG8_WAIT_L(0); PG8_BAR; PG8_MMA(1, 0, At, B0); PG8_MMA(1, 1, At, B1); PG8_BAR; PG8_SCHED;
;     ...
;         if constexpr (ALIGN_EPI) { if (wr == 0) PG8_BAR; }
	s_add_i32 s62, s62, s3
	v_lshl_add_u64 v[166:167], v[166:167], 0, s[8:9]
	s_mov_b32 m0, s62
	ds_read_b128 v[210:213], v145 offset:49152
	ds_read_b128 v[214:217], v145 offset:50176
	ds_read_b128 v[218:221], v145 offset:51200
	ds_read_b128 v[222:225], v145 offset:52224
	ds_read_b128 v[226:229], v145 offset:53248
	ds_read_b128 v[230:233], v145 offset:54272
	ds_read_b128 v[234:237], v145 offset:55296
	ds_read_b128 v[238:241], v145 offset:56320
	global_load_lds_dwordx4 v[166:167], off
	s_add_i32 m0, s62, 0x2000
	s_add_u32 s78, s78, 0x80080
	v_lshl_add_u64 v[166:167], v[242:243], 0, s[8:9]
	s_addc_u32 s79, s79, 0
	s_add_i32 s62, s63, s3
	global_load_lds_dwordx4 v[166:167], off
	v_lshl_add_u64 v[166:167], s[78:79], 0, v[130:131]
	s_mov_b32 m0, s62
	s_nop 0
	global_load_lds_dwordx4 v[166:167], off
	v_lshl_add_u64 v[166:167], s[78:79], 0, v[134:135]
	s_add_i32 m0, s62, 0x2000
	s_nop 0
	global_load_lds_dwordx4 v[166:167], off
	v_lshl_add_u64 v[166:167], v[244:245], 0, s[8:9]
	s_mov_b32 m0, s89
	s_nop 0
	global_load_lds_dwordx4 v[166:167], off
	v_lshl_add_u64 v[166:167], v[246:247], 0, s[8:9]
	s_mov_b32 m0, s90
	s_nop 0
	global_load_lds_dwordx4 v[166:167], off
	s_waitcnt vmcnt(8)
	s_waitcnt lgkmcnt(0)
	s_barrier
	s_setprio 1
	s_waitcnt lgkmcnt(0)
	v_mfma_f32_16x16x32_bf16 v[92:95], v[178:181], v[210:213], v[92:95]
	v_mfma_f32_16x16x32_bf16 v[92:95], v[182:185], v[214:217], v[92:95]
	v_mfma_f32_16x16x32_bf16 v[88:91], v[186:189], v[210:213], v[88:91]
	v_mfma_f32_16x16x32_bf16 v[88:91], v[190:193], v[214:217], v[88:91]
	v_mfma_f32_16x16x32_bf16 v[80:83], v[186:189], v[218:221], v[80:83]
	v_mfma_f32_16x16x32_bf16 v[80:83], v[190:193], v[222:225], v[80:83]
	v_mfma_f32_16x16x32_bf16 v[84:87], v[178:181], v[218:221], v[84:87]
	v_mfma_f32_16x16x32_bf16 v[84:87], v[182:185], v[222:225], v[84:87]
	v_mfma_f32_16x16x32_bf16 v[76:79], v[178:181], v[226:229], v[76:79]
	v_mfma_f32_16x16x32_bf16 v[76:79], v[182:185], v[230:233], v[76:79]
	v_mfma_f32_16x16x32_bf16 v[72:75], v[186:189], v[226:229], v[72:75]
	v_mfma_f32_16x16x32_bf16 v[72:75], v[190:193], v[230:233], v[72:75]
	v_mfma_f32_16x16x32_bf16 v[56:59], v[186:189], v[234:237], v[56:59]
	v_mfma_f32_16x16x32_bf16 v[56:59], v[190:193], v[238:241], v[56:59]
	v_mfma_f32_16x16x32_bf16 v[60:63], v[178:181], v[234:237], v[60:63]
	v_mfma_f32_16x16x32_bf16 v[60:63], v[182:185], v[238:241], v[60:63]
	s_setprio 0
	s_setprio 1
	v_mfma_f32_16x16x32_bf16 v[28:31], v[194:197], v[210:213], v[28:31]
	v_mfma_f32_16x16x32_bf16 v[28:31], v[198:201], v[214:217], v[28:31]
	v_mfma_f32_16x16x32_bf16 v[24:27], v[202:205], v[210:213], v[24:27]
	v_mfma_f32_16x16x32_bf16 v[24:27], v[206:209], v[214:217], v[24:27]
	v_mfma_f32_16x16x32_bf16 v[16:19], v[202:205], v[218:221], v[16:19]
	v_mfma_f32_16x16x32_bf16 v[16:19], v[206:209], v[222:225], v[16:19]
	v_mfma_f32_16x16x32_bf16 v[20:23], v[194:197], v[218:221], v[20:23]
	v_mfma_f32_16x16x32_bf16 v[20:23], v[198:201], v[222:225], v[20:23]
	v_mfma_f32_16x16x32_bf16 v[12:15], v[194:197], v[226:229], v[12:15]
	v_mfma_f32_16x16x32_bf16 v[12:15], v[198:201], v[230:233], v[12:15]
	v_mfma_f32_16x16x32_bf16 v[8:11], v[202:205], v[226:229], v[8:11]
	v_mfma_f32_16x16x32_bf16 v[8:11], v[206:209], v[230:233], v[8:11]
	v_mfma_f32_16x16x32_bf16 v[0:3], v[202:205], v[234:237], v[0:3]
	v_mfma_f32_16x16x32_bf16 v[0:3], v[206:209], v[238:241], v[0:3]
	v_mfma_f32_16x16x32_bf16 v[4:7], v[194:197], v[234:237], v[4:7]
	v_mfma_f32_16x16x32_bf16 v[4:7], v[198:201], v[238:241], v[4:7]
	s_setprio 0
	s_barrier
	s_add_i32 s75, s75, 2
	s_add_u32 s76, s76, 0x100
	s_addc_u32 s77, s77, 0
	s_add_u32 s57, s57, 0x100
	s_addc_u32 s67, s67, 0
	s_cmp_gt_u32 s75, 29
	s_cbranch_scc0 .LBB0_326
	s_and_b64 vcc, exec, s[20:21]
	s_cbranch_vccz .LBB0_329
	s_barrier

; #define PG8_STAGE(bufoff, gbase, voff) do { _Pragma("unroll") for (int _i = 0; _i < 2; ++_i) \
;         __builtin_amdgcn_global_load_lds((const unsigned*)((const char*)(gbase) + (voff)[_i]), (PG8_LAS unsigned*)(lds + (bufoff) + ldsw + _i * 8192), 16, 0, 0); } while (0)
; #define PG8_LDA(dst, b, h) do { _Pragma("unroll") for (int m = 0; m < 4; ++m) _Pragma("unroll") for (int k = 0; k < 2; ++k) dst[m][k] = *(const PG8_LAS bf16x8*)(lds + PG8_SA(b, h) + aoff + m * 2048 + k * 1024); } while (0)
; #define PG8_LDB(dst, b, h) do { _Pragma("unroll") for (int n = 0; n < 2; ++n) _Pragma("unroll") for (int k = 0; k < 2; ++k) dst[n][k] = *(const PG8_LAS bf16x8*)(lds + PG8_SB(b, h) + boff + n * 2048 + k * 1024); } while (0)
; #define PG8_MMA(ai, bj, At, Bt) do { __builtin_amdgcn_s_setprio(1); _Pragma("unroll") for (int m = 0; m < 4; ++m) _Pragma("unroll") for (int n = 0; n < 2; ++n) _Pragma("unroll") for (int k = 0; k < 2; ++k) \
;         acc[ai][bj][m][n] = __builtin_amdgcn_mfma_f32_16x16x32_bf16(Bt[n][k], At[m][k], acc[ai][bj][m][n], 0, 0, 0); __builtin_amdgcn_s_setprio(0); } while (0)
; #define PG8_WAIT_V(n) asm volatile("s_waitcnt vmcnt(" #n ")" ::: "memory")
; #define PG8_WAIT_L(n) asm volatile("s_waitcnt lgkmcnt(" #n ")" ::: "memory")
; template <class Epi, class Sched, bool ALIGN_EPI = false, bool SP2 = false>
; __device__ __forceinline__ void gemm_phase(PG8_LAS unsigned char* lds, const Gemm g, const Sched& S, const Epi& E) {
;     ...
;             const bool last = (t == nt - 2);
;             const char* a1 = cA + (size_t)(t + 1) * kstep;
;             const char* a2 = last ? nA : cA + (size_t)(t + 2) * kstep; const char* b2 = last ? nB : cB + (size_t)(t + 2) * kstep;
;             const char* a3 = a2 + kstep; const char* b3 = b2 + kstep;
;             if (last && has_next) S.a_ready(nxt);
;             if constexpr (SP2) {
;             PG8_LDB(B0, 0, 0); PG8_LDB(B1, 0, 1); PG8_SCHED; PG8_LDA(At, 0, 0); PG8_STAGE(PG8_SA(1, 1), a1 + hstep, voffA);
;             PG8_WAIT_V(8); PG8_WAIT_L(0); PG8_BAR; PG8_MMA(0, 0, At, B0); PG8_MMA(0, 1, At, B1); PG8_BAR; PG8_SCHED;
;             PG8_LDA(At, 0, 1); PG8_STAGE(PG8_SB(0, 0), b2, voffB); PG8_STAGE(PG8_SB(0, 1), b2 + hstep, voffB); PG8_STAGE(PG8_SA(0, 0), a2, voffA);
;             PG8_WAIT_V(8); PG8_WAIT_L(0); PG8_BAR; PG8_MMA(1, 0, At, B0); PG8_MMA(1, 1, At, B1); PG8_BAR; PG8_SCHED;
.LBB0_557:
	ds_read_b128 v[144:147], v155
	ds_read_b128 v[160:163], v155 offset:1024
	ds_read_b128 v[164:167], v155 offset:2048
	ds_read_b128 v[168:171], v155 offset:3072
	ds_read_b128 v[172:175], v156
	ds_read_b128 v[176:179], v156 offset:1024
	ds_read_b128 v[180:183], v156 offset:2048
	ds_read_b128 v[184:187], v156 offset:3072
	s_add_u32 s54, s50, 0xfff80080
	s_addc_u32 s55, s51, -1
	s_cmp_eq_u32 s73, 28
	s_cselect_b32 s57, s10, s55
	s_cselect_b32 s56, s11, s54
	s_cselect_b32 s55, s41, s72
	s_cselect_b32 s54, s43, s49
	v_lshl_add_u64 v[220:221], s[50:51], 0, v[136:137]
	s_add_i32 m0, s33, 0xc000
	ds_read_b128 v[188:191], v157
	ds_read_b128 v[192:195], v157 offset:1024
	ds_read_b128 v[196:199], v157 offset:2048
	ds_read_b128 v[200:203], v157 offset:3072
	ds_read_b128 v[204:207], v157 offset:4096
	ds_read_b128 v[208:211], v157 offset:5120
	ds_read_b128 v[212:215], v157 offset:6144
	ds_read_b128 v[216:219], v157 offset:7168
	global_load_lds_dwordx4 v[220:221], off
	v_lshl_add_u64 v[220:221], s[50:51], 0, v[138:139]
	s_add_i32 m0, s33, 0xe000
	s_nop 0
	global_load_lds_dwordx4 v[220:221], off
	s_waitcnt vmcnt(8)
	s_waitcnt lgkmcnt(0)
	s_barrier
	s_setprio 1
	s_waitcnt lgkmcnt(0)
	v_mfma_f32_16x16x32_bf16 v[124:127], v[144:147], v[188:191], v[124:127]
	v_mfma_f32_16x16x32_bf16 v[124:127], v[160:163], v[192:195], v[124:127]
	v_mfma_f32_16x16x32_bf16 v[120:123], v[164:167], v[188:191], v[120:123]
	v_mfma_f32_16x16x32_bf16 v[120:123], v[168:171], v[192:195], v[120:123]
	v_mfma_f32_16x16x32_bf16 v[104:107], v[164:167], v[196:199], v[104:107]
	v_mfma_f32_16x16x32_bf16 v[104:107], v[168:171], v[200:203], v[104:107]
	v_mfma_f32_16x16x32_bf16 v[108:111], v[144:147], v[196:199], v[108:111]
	v_mfma_f32_16x16x32_bf16 v[108:111], v[160:163], v[200:203], v[108:111]
	v_mfma_f32_16x16x32_bf16 v[92:95], v[144:147], v[204:207], v[92:95]
	v_mfma_f32_16x16x32_bf16 v[92:95], v[160:163], v[208:211], v[92:95]
	v_mfma_f32_16x16x32_bf16 v[88:91], v[164:167], v[204:207], v[88:91]
	v_mfma_f32_16x16x32_bf16 v[88:91], v[168:171], v[208:211], v[88:91]
	v_mfma_f32_16x16x32_bf16 v[72:75], v[164:167], v[212:215], v[72:75]
	v_mfma_f32_16x16x32_bf16 v[72:75], v[168:171], v[216:219], v[72:75]
	v_mfma_f32_16x16x32_bf16 v[76:79], v[144:147], v[212:215], v[76:79]
	v_mfma_f32_16x16x32_bf16 v[76:79], v[160:163], v[216:219], v[76:79]
	s_setprio 0
	s_setprio 1
	v_mfma_f32_16x16x32_bf16 v[116:119], v[172:175], v[188:191], v[116:119]
	v_mfma_f32_16x16x32_bf16 v[116:119], v[176:179], v[192:195], v[116:119]
	v_mfma_f32_16x16x32_bf16 v[112:115], v[180:183], v[188:191], v[112:115]
	v_mfma_f32_16x16x32_bf16 v[112:115], v[184:187], v[192:195], v[112:115]
	v_mfma_f32_16x16x32_bf16 v[96:99], v[180:183], v[196:199], v[96:99]
	v_mfma_f32_16x16x32_bf16 v[96:99], v[184:187], v[200:203], v[96:99]
	v_mfma_f32_16x16x32_bf16 v[100:103], v[172:175], v[196:199], v[100:103]
	v_mfma_f32_16x16x32_bf16 v[100:103], v[176:179], v[200:203], v[100:103]
	v_mfma_f32_16x16x32_bf16 v[84:87], v[172:175], v[204:207], v[84:87]
	v_mfma_f32_16x16x32_bf16 v[84:87], v[176:179], v[208:211], v[84:87]
	v_mfma_f32_16x16x32_bf16 v[80:83], v[180:183], v[204:207], v[80:83]
	v_mfma_f32_16x16x32_bf16 v[80:83], v[184:187], v[208:211], v[80:83]
	v_mfma_f32_16x16x32_bf16 v[64:67], v[180:183], v[212:215], v[64:67]
	v_mfma_f32_16x16x32_bf16 v[64:67], v[184:187], v[216:219], v[64:67]
	v_mfma_f32_16x16x32_bf16 v[68:71], v[172:175], v[212:215], v[68:71]
	v_mfma_f32_16x16x32_bf16 v[68:71], v[176:179], v[216:219], v[68:71]
	s_setprio 0
	s_barrier
	s_add_i32 s62, s67, s3
	v_lshl_add_u64 v[220:221], s[54:55], 0, v[130:131]
	s_mov_b32 m0, s62
	ds_read_b128 v[188:191], v157 offset:16384
	ds_read_b128 v[192:195], v157 offset:17408
	ds_read_b128 v[196:199], v157 offset:18432
	ds_read_b128 v[200:203], v157 offset:19456
	ds_read_b128 v[204:207], v157 offset:20480
	ds_read_b128 v[208:211], v157 offset:21504
	ds_read_b128 v[212:215], v157 offset:22528
	ds_read_b128 v[216:219], v157 offset:23552
	global_load_lds_dwordx4 v[220:221], off
	s_add_i32 m0, s62, 0x2000
	s_add_u32 s62, s54, 0x80000
	v_lshl_add_u64 v[222:223], s[54:55], 0, v[134:135]
	s_addc_u32 s63, s55, 0
	s_add_i32 s74, s70, s3
	global_load_lds_dwordx4 v[222:223], off
	v_lshl_add_u64 v[224:225], s[62:63], 0, v[130:131]
	s_mov_b32 m0, s74
	v_lshl_add_u64 v[226:227], s[56:57], 0, v[132:133]
	global_load_lds_dwordx4 v[224:225], off
	v_lshl_add_u64 v[224:225], s[62:63], 0, v[134:135]
	s_add_i32 m0, s74, 0x2000
	s_nop 0
	global_load_lds_dwordx4 v[224:225], off
	v_lshl_add_u64 v[224:225], s[56:57], 0, v[128:129]
	s_mov_b32 m0, s33
	s_nop 0
	global_load_lds_dwordx4 v[224:225], off
	s_mov_b32 m0, s35
	s_nop 0
	global_load_lds_dwordx4 v[226:227], off
	s_waitcnt vmcnt(8)
	s_waitcnt lgkmcnt(0)
	s_barrier
; #define PG8_STAGE(bufoff, gbase, voff) do { _Pragma("unroll") for (int _i = 0; _i < 2; ++_i) \
;         __builtin_amdgcn_global_load_lds((const unsigned*)((const char*)(gbase) + (voff)[_i]), (PG8_LAS unsigned*)(lds + (bufoff) + ldsw + _i * 8192), 16, 0, 0); } while (0)
; #define PG8_LDA(dst, b, h) do { _Pragma("unroll") for (int m = 0; m < 4; ++m) _Pragma("unroll") for (int k = 0; k < 2; ++k) dst[m][k] = *(const PG8_LAS bf16x8*)(lds + PG8_SA(b, h) + aoff + m * 2048 + k * 1024); } while (0)
; #define PG8_LDB(dst, b, h) do { _Pragma("unroll") for (int n = 0; n < 2; ++n) _Pragma("unroll") for (int k = 0; k < 2; ++k) dst[n][k] = *(const PG8_LAS bf16x8*)(lds + PG8_SB(b, h) + boff + n * 2048 + k * 1024); } while (0)
; #define PG8_MMA(ai, bj, At, Bt) do { __builtin_amdgcn_s_setprio(1); _Pragma("unroll") for (int m = 0; m < 4; ++m) _Pragma("unroll") for (int n = 0; n < 2; ++n) _Pragma("unroll") for (int k = 0; k < 2; ++k) \
;         acc[ai][bj][m][n] = __builtin_amdgcn_mfma_f32_16x16x32_bf16(Bt[n][k], At[m][k], acc[ai][bj][m][n], 0, 0, 0); __builtin_amdgcn_s_setprio(0); } while (0)
; #define PG8_WAIT_V(n) asm volatile("s_waitcnt vmcnt(" #n ")" ::: "memory")
; #define PG8_WAIT_L(n) asm volatile("s_waitcnt lgkmcnt(" #n ")" ::: "memory")
; #define PG8_BAR __builtin_amdgcn_s_barrier()
; #define PG8_SCHED __builtin_amdgcn_sched_barrier(0)
; template <class Epi, class Sched, bool ALIGN_EPI = false, bool SP2 = false>
; __device__ __forceinline__ void gemm_phase(PG8_LAS unsigned char* lds, const Gemm g, const Sched& S, const Epi& E) {
;     ...
;             PG8_WAIT_V(8); PG8_WAIT_L(0); PG8_BAR; PG8_MMA(1, 0, At, B0); PG8_MMA(1, 1, At, B1); PG8_BAR; PG8_SCHED;
;             PG8_LDB(B0, 1, 0); PG8_LDB(B1, 1, 1); PG8_SCHED; PG8_LDA(At, 1, 0); PG8_STAGE(PG8_SA(0, 1), a2 + hstep, voffA);
;             PG8_WAIT_V(8); PG8_WAIT_L(0); PG8_BAR; PG8_MMA(0, 0, At, B0); PG8_MMA(0, 1, At, B1); PG8_BAR; PG8_SCHED;
	s_setprio 1
	s_waitcnt lgkmcnt(0)
	v_mfma_f32_16x16x32_bf16 v[60:63], v[144:147], v[188:191], v[60:63]
	v_mfma_f32_16x16x32_bf16 v[60:63], v[160:163], v[192:195], v[60:63]
	v_mfma_f32_16x16x32_bf16 v[56:59], v[164:167], v[188:191], v[56:59]
	v_mfma_f32_16x16x32_bf16 v[56:59], v[168:171], v[192:195], v[56:59]
	v_mfma_f32_16x16x32_bf16 v[40:43], v[164:167], v[196:199], v[40:43]
	v_mfma_f32_16x16x32_bf16 v[40:43], v[168:171], v[200:203], v[40:43]
	v_mfma_f32_16x16x32_bf16 v[44:47], v[144:147], v[196:199], v[44:47]
	v_mfma_f32_16x16x32_bf16 v[44:47], v[160:163], v[200:203], v[44:47]
	v_mfma_f32_16x16x32_bf16 v[28:31], v[144:147], v[204:207], v[28:31]
	v_mfma_f32_16x16x32_bf16 v[28:31], v[160:163], v[208:211], v[28:31]
	v_mfma_f32_16x16x32_bf16 v[24:27], v[164:167], v[204:207], v[24:27]
	v_mfma_f32_16x16x32_bf16 v[24:27], v[168:171], v[208:211], v[24:27]
	v_mfma_f32_16x16x32_bf16 v[8:11], v[164:167], v[212:215], v[8:11]
	v_mfma_f32_16x16x32_bf16 v[8:11], v[168:171], v[216:219], v[8:11]
	v_mfma_f32_16x16x32_bf16 v[12:15], v[144:147], v[212:215], v[12:15]
	v_mfma_f32_16x16x32_bf16 v[12:15], v[160:163], v[216:219], v[12:15]
	s_setprio 0
	s_setprio 1
	v_mfma_f32_16x16x32_bf16 v[52:55], v[172:175], v[188:191], v[52:55]
	v_mfma_f32_16x16x32_bf16 v[52:55], v[176:179], v[192:195], v[52:55]
	v_mfma_f32_16x16x32_bf16 v[48:51], v[180:183], v[188:191], v[48:51]
	v_mfma_f32_16x16x32_bf16 v[48:51], v[184:187], v[192:195], v[48:51]
	v_mfma_f32_16x16x32_bf16 v[32:35], v[180:183], v[196:199], v[32:35]
	v_mfma_f32_16x16x32_bf16 v[32:35], v[184:187], v[200:203], v[32:35]
	v_mfma_f32_16x16x32_bf16 v[36:39], v[172:175], v[196:199], v[36:39]
	v_mfma_f32_16x16x32_bf16 v[36:39], v[176:179], v[200:203], v[36:39]
	v_mfma_f32_16x16x32_bf16 v[20:23], v[172:175], v[204:207], v[20:23]
	v_mfma_f32_16x16x32_bf16 v[20:23], v[176:179], v[208:211], v[20:23]
	v_mfma_f32_16x16x32_bf16 v[16:19], v[180:183], v[204:207], v[16:19]
	v_mfma_f32_16x16x32_bf16 v[16:19], v[184:187], v[208:211], v[16:19]
	v_mfma_f32_16x16x32_bf16 v[0:3], v[180:183], v[212:215], v[0:3]
	v_mfma_f32_16x16x32_bf16 v[0:3], v[184:187], v[216:219], v[0:3]
	v_mfma_f32_16x16x32_bf16 v[4:7], v[172:175], v[212:215], v[4:7]
	v_mfma_f32_16x16x32_bf16 v[4:7], v[176:179], v[216:219], v[4:7]
	s_setprio 0
	s_barrier
	s_add_i32 s62, 0, 0x18000
	v_add_u32_e32 v159, s62, v153
	s_add_i32 s63, 0, 0x1c000
	ds_read_b128 v[144:147], v159
	ds_read_b128 v[160:163], v159 offset:1024
	ds_read_b128 v[164:167], v159 offset:2048
	ds_read_b128 v[168:171], v159 offset:3072
	v_add_u32_e32 v159, s63, v153
	ds_read_b128 v[172:175], v159
	ds_read_b128 v[176:179], v159 offset:1024
	ds_read_b128 v[180:183], v159 offset:2048
	ds_read_b128 v[184:187], v159 offset:3072
	s_add_u32 s56, s56, 0x80000
	s_addc_u32 s57, s57, 0
	s_mov_b32 m0, s52
	v_lshl_add_u64 v[228:229], s[56:57], 0, v[128:129]
	ds_read_b128 v[188:191], v157 offset:32768
	ds_read_b128 v[192:195], v157 offset:33792
	ds_read_b128 v[196:199], v157 offset:34816
	ds_read_b128 v[200:203], v157 offset:35840
	ds_read_b128 v[204:207], v157 offset:36864
	ds_read_b128 v[208:211], v157 offset:37888
	ds_read_b128 v[212:215], v157 offset:38912
	ds_read_b128 v[216:219], v157 offset:39936
	global_load_lds_dwordx4 v[228:229], off
	v_lshl_add_u64 v[228:229], s[56:57], 0, v[132:133]
	s_mov_b32 m0, s53
	s_nop 0
	global_load_lds_dwordx4 v[228:229], off
	s_waitcnt vmcnt(8)
	s_waitcnt lgkmcnt(0)
	s_barrier
	s_setprio 1
	s_waitcnt lgkmcnt(0)
	v_mfma_f32_16x16x32_bf16 v[124:127], v[144:147], v[188:191], v[124:127]
	v_mfma_f32_16x16x32_bf16 v[124:127], v[160:163], v[192:195], v[124:127]
	v_mfma_f32_16x16x32_bf16 v[120:123], v[164:167], v[188:191], v[120:123]
	v_mfma_f32_16x16x32_bf16 v[120:123], v[168:171], v[192:195], v[120:123]
	v_mfma_f32_16x16x32_bf16 v[104:107], v[164:167], v[196:199], v[104:107]
	v_mfma_f32_16x16x32_bf16 v[104:107], v[168:171], v[200:203], v[104:107]
	v_mfma_f32_16x16x32_bf16 v[108:111], v[144:147], v[196:199], v[108:111]
	v_mfma_f32_16x16x32_bf16 v[108:111], v[160:163], v[200:203], v[108:111]
	v_mfma_f32_16x16x32_bf16 v[92:95], v[144:147], v[204:207], v[92:95]
	v_mfma_f32_16x16x32_bf16 v[92:95], v[160:163], v[208:211], v[92:95]
	v_mfma_f32_16x16x32_bf16 v[88:91], v[164:167], v[204:207], v[88:91]
	v_mfma_f32_16x16x32_bf16 v[88:91], v[168:171], v[208:211], v[88:91]
	v_mfma_f32_16x16x32_bf16 v[72:75], v[164:167], v[212:215], v[72:75]
	v_mfma_f32_16x16x32_bf16 v[72:75], v[168:171], v[216:219], v[72:75]
	v_mfma_f32_16x16x32_bf16 v[76:79], v[144:147], v[212:215], v[76:79]
	v_mfma_f32_16x16x32_bf16 v[76:79], v[160:163], v[216:219], v[76:79]
	s_setprio 0
	s_setprio 1
	v_mfma_f32_16x16x32_bf16 v[116:119], v[172:175], v[188:191], v[116:119]
	v_mfma_f32_16x16x32_bf16 v[116:119], v[176:179], v[192:195], v[116:119]
	v_mfma_f32_16x16x32_bf16 v[112:115], v[180:183], v[188:191], v[112:115]
	v_mfma_f32_16x16x32_bf16 v[112:115], v[184:187], v[192:195], v[112:115]
	v_mfma_f32_16x16x32_bf16 v[96:99], v[180:183], v[196:199], v[96:99]
	v_mfma_f32_16x16x32_bf16 v[96:99], v[184:187], v[200:203], v[96:99]
	v_mfma_f32_16x16x32_bf16 v[100:103], v[172:175], v[196:199], v[100:103]
	v_mfma_f32_16x16x32_bf16 v[100:103], v[176:179], v[200:203], v[100:103]
	v_mfma_f32_16x16x32_bf16 v[84:87], v[172:175], v[204:207], v[84:87]
	v_mfma_f32_16x16x32_bf16 v[84:87], v[176:179], v[208:211], v[84:87]
	v_mfma_f32_16x16x32_bf16 v[80:83], v[180:183], v[204:207], v[80:83]
	v_mfma_f32_16x16x32_bf16 v[80:83], v[184:187], v[208:211], v[80:83]
	v_mfma_f32_16x16x32_bf16 v[64:67], v[180:183], v[212:215], v[64:67]
	v_mfma_f32_16x16x32_bf16 v[64:67], v[184:187], v[216:219], v[64:67]
	v_mfma_f32_16x16x32_bf16 v[68:71], v[172:175], v[212:215], v[68:71]
	v_mfma_f32_16x16x32_bf16 v[68:71], v[176:179], v[216:219], v[68:71]
	s_setprio 0
	s_barrier
; #define PG8_STAGE(bufoff, gbase, voff) do { _Pragma("unroll") for (int _i = 0; _i < 2; ++_i) \
;         __builtin_amdgcn_global_load_lds((const unsigned*)((const char*)(gbase) + (voff)[_i]), (PG8_LAS unsigned*)(lds + (bufoff) + ldsw + _i * 8192), 16, 0, 0); } while (0)
; #define PG8_LDA(dst, b, h) do { _Pragma("unroll") for (int m = 0; m < 4; ++m) _Pragma("unroll") for (int k = 0; k < 2; ++k) dst[m][k] = *(const PG8_LAS bf16x8*)(lds + PG8_SA(b, h) + aoff + m * 2048 + k * 1024); } while (0)
; #define PG8_MMA(ai, bj, At, Bt) do { __builtin_amdgcn_s_setprio(1); _Pragma("unroll") for (int m = 0; m < 4; ++m) _Pragma("unroll") for (int n = 0; n < 2; ++n) _Pragma("unroll") for (int k = 0; k < 2; ++k) \
;         acc[ai][bj][m][n] = __builtin_amdgcn_mfma_f32_16x16x32_bf16(Bt[n][k], At[m][k], acc[ai][bj][m][n], 0, 0, 0); __builtin_amdgcn_s_setprio(0); } while (0)
; #define PG8_WAIT_V(n) asm volatile("s_waitcnt vmcnt(" #n ")" ::: "memory")
; #define PG8_WAIT_L(n) asm volatile("s_waitcnt lgkmcnt(" #n ")" ::: "memory")
; #define PG8_BAR __builtin_amdgcn_s_barrier()
; #define PG8_SCHED __builtin_amdgcn_sched_barrier(0)
; template <class Epi, class Sched, bool ALIGN_EPI = false, bool SP2 = false>
; __device__ __forceinline__ void gemm_phase(PG8_LAS unsigned char* lds, const Gemm g, const Sched& S, const Epi& E) {
;     ...
;             PG8_LDA(At, 1, 1); PG8_STAGE(PG8_SB(1, 0), b3, voffB); PG8_STAGE(PG8_SB(1, 1), b3 + hstep, voffB); PG8_STAGE(PG8_SA(1, 0), a3, voffA);
;             PG8_WAIT_V(8); PG8_WAIT_L(0); PG8_BAR; PG8_MMA(1, 0, At, B0); PG8_MMA(1, 1, At, B1); PG8_BAR; PG8_SCHED;
;     ...
;         if constexpr (ALIGN_EPI) { if (wr == 0) PG8_BAR; }
	s_add_i32 s56, s62, s3
	v_lshl_add_u64 v[220:221], v[220:221], 0, s[20:21]
	s_mov_b32 m0, s56
	ds_read_b128 v[188:191], v157 offset:49152
	ds_read_b128 v[192:195], v157 offset:50176
	ds_read_b128 v[196:199], v157 offset:51200
	ds_read_b128 v[200:203], v157 offset:52224
	ds_read_b128 v[204:207], v157 offset:53248
	ds_read_b128 v[208:211], v157 offset:54272
	ds_read_b128 v[212:215], v157 offset:55296
	ds_read_b128 v[216:219], v157 offset:56320
	global_load_lds_dwordx4 v[220:221], off
	s_add_i32 m0, s56, 0x2000
	s_add_u32 s54, s54, 0x80080
	v_lshl_add_u64 v[220:221], v[222:223], 0, s[20:21]
	s_addc_u32 s55, s55, 0
	s_add_i32 s56, s63, s3
	global_load_lds_dwordx4 v[220:221], off
	v_lshl_add_u64 v[220:221], s[54:55], 0, v[130:131]
	s_mov_b32 m0, s56
	s_nop 0
	global_load_lds_dwordx4 v[220:221], off
	v_lshl_add_u64 v[220:221], s[54:55], 0, v[134:135]
	s_add_i32 m0, s56, 0x2000
	s_nop 0
	global_load_lds_dwordx4 v[220:221], off
	v_lshl_add_u64 v[220:221], v[224:225], 0, s[20:21]
	s_mov_b32 m0, s64
	s_nop 0
	global_load_lds_dwordx4 v[220:221], off
	v_lshl_add_u64 v[220:221], v[226:227], 0, s[20:21]
	s_mov_b32 m0, s65
	s_nop 0
	global_load_lds_dwordx4 v[220:221], off
	s_waitcnt vmcnt(8)
	s_waitcnt lgkmcnt(0)
	s_barrier
	s_setprio 1
	s_waitcnt lgkmcnt(0)
	v_mfma_f32_16x16x32_bf16 v[60:63], v[144:147], v[188:191], v[60:63]
	v_mfma_f32_16x16x32_bf16 v[60:63], v[160:163], v[192:195], v[60:63]
	v_mfma_f32_16x16x32_bf16 v[56:59], v[164:167], v[188:191], v[56:59]
	v_mfma_f32_16x16x32_bf16 v[56:59], v[168:171], v[192:195], v[56:59]
	v_mfma_f32_16x16x32_bf16 v[40:43], v[164:167], v[196:199], v[40:43]
	v_mfma_f32_16x16x32_bf16 v[40:43], v[168:171], v[200:203], v[40:43]
	v_mfma_f32_16x16x32_bf16 v[44:47], v[144:147], v[196:199], v[44:47]
	v_mfma_f32_16x16x32_bf16 v[44:47], v[160:163], v[200:203], v[44:47]
	v_mfma_f32_16x16x32_bf16 v[28:31], v[144:147], v[204:207], v[28:31]
	v_mfma_f32_16x16x32_bf16 v[28:31], v[160:163], v[208:211], v[28:31]
	v_mfma_f32_16x16x32_bf16 v[24:27], v[164:167], v[204:207], v[24:27]
	v_mfma_f32_16x16x32_bf16 v[24:27], v[168:171], v[208:211], v[24:27]
	v_mfma_f32_16x16x32_bf16 v[8:11], v[164:167], v[212:215], v[8:11]
	v_mfma_f32_16x16x32_bf16 v[8:11], v[168:171], v[216:219], v[8:11]
	v_mfma_f32_16x16x32_bf16 v[12:15], v[144:147], v[212:215], v[12:15]
	v_mfma_f32_16x16x32_bf16 v[12:15], v[160:163], v[216:219], v[12:15]
	s_setprio 0
	s_setprio 1
	v_mfma_f32_16x16x32_bf16 v[52:55], v[172:175], v[188:191], v[52:55]
	v_mfma_f32_16x16x32_bf16 v[52:55], v[176:179], v[192:195], v[52:55]
	v_mfma_f32_16x16x32_bf16 v[48:51], v[180:183], v[188:191], v[48:51]
	v_mfma_f32_16x16x32_bf16 v[48:51], v[184:187], v[192:195], v[48:51]
	v_mfma_f32_16x16x32_bf16 v[32:35], v[180:183], v[196:199], v[32:35]
	v_mfma_f32_16x16x32_bf16 v[32:35], v[184:187], v[200:203], v[32:35]
	v_mfma_f32_16x16x32_bf16 v[36:39], v[172:175], v[196:199], v[36:39]
	v_mfma_f32_16x16x32_bf16 v[36:39], v[176:179], v[200:203], v[36:39]
	v_mfma_f32_16x16x32_bf16 v[20:23], v[172:175], v[204:207], v[20:23]
	v_mfma_f32_16x16x32_bf16 v[20:23], v[176:179], v[208:211], v[20:23]
	v_mfma_f32_16x16x32_bf16 v[16:19], v[180:183], v[204:207], v[16:19]
	v_mfma_f32_16x16x32_bf16 v[16:19], v[184:187], v[208:211], v[16:19]
	v_mfma_f32_16x16x32_bf16 v[0:3], v[180:183], v[212:215], v[0:3]
	v_mfma_f32_16x16x32_bf16 v[0:3], v[184:187], v[216:219], v[0:3]
	v_mfma_f32_16x16x32_bf16 v[4:7], v[172:175], v[212:215], v[4:7]
	v_mfma_f32_16x16x32_bf16 v[4:7], v[176:179], v[216:219], v[4:7]
	s_setprio 0
	s_barrier
	s_add_i32 s73, s73, 2
	s_add_u32 s50, s50, 0x100
	s_addc_u32 s51, s51, 0
	s_add_u32 s49, s49, 0x100
	s_addc_u32 s72, s72, 0
	s_cmp_gt_u32 s73, 29
	s_cbranch_scc0 .LBB0_557
	s_and_b64 vcc, exec, s[38:39]
	s_cbranch_vccz .LBB0_560
	s_barrier

; #define PG8_STAGE(bufoff, gbase, voff) do { _Pragma("unroll") for (int _i = 0; _i < 2; ++_i) \
;         __builtin_amdgcn_global_load_lds((const unsigned*)((const char*)(gbase) + (voff)[_i]), (PG8_LAS unsigned*)(lds + (bufoff) + ldsw + _i * 8192), 16, 0, 0); } while (0)
; #define PG8_LDA(dst, b, h) do { _Pragma("unroll") for (int m = 0; m < 4; ++m) _Pragma("unroll") for (int k = 0; k < 2; ++k) dst[m][k] = *(const PG8_LAS bf16x8*)(lds + PG8_SA(b, h) + aoff + m * 2048 + k * 1024); } while (0)
; #define PG8_LDB(dst, b, h) do { _Pragma("unroll") for (int n = 0; n < 2; ++n) _Pragma("unroll") for (int k = 0; k < 2; ++k) dst[n][k] = *(const PG8_LAS bf16x8*)(lds + PG8_SB(b, h) + boff + n * 2048 + k * 1024); } while (0)
; #define PG8_MMA(ai, bj, At, Bt) do { __builtin_amdgcn_s_setprio(1); _Pragma("unroll") for (int m = 0; m < 4; ++m) _Pragma("unroll") for (int n = 0; n < 2; ++n) _Pragma("unroll") for (int k = 0; k < 2; ++k) \
;         acc[ai][bj][m][n] = __builtin_amdgcn_mfma_f32_16x16x32_bf16(Bt[n][k], At[m][k], acc[ai][bj][m][n], 0, 0, 0); __builtin_amdgcn_s_setprio(0); } while (0)
; #define PG8_WAIT_V(n) asm volatile("s_waitcnt vmcnt(" #n ")" ::: "memory")
; #define PG8_WAIT_L(n) asm volatile("s_waitcnt lgkmcnt(" #n ")" ::: "memory")
; template <class Epi, class Sched, bool ALIGN_EPI = false, bool SP2 = false>
; __device__ __forceinline__ void gemm_phase(PG8_LAS unsigned char* lds, const Gemm g, const Sched& S, const Epi& E) {
;     ...
;             const bool last = (t == nt - 2);
;             const char* a1 = cA + (size_t)(t + 1) * kstep;
;             const char* a2 = last ? nA : cA + (size_t)(t + 2) * kstep; const char* b2 = last ? nB : cB + (size_t)(t + 2) * kstep;
;             const char* a3 = a2 + kstep; const char* b3 = b2 + kstep;
;             if (last && has_next) S.a_ready(nxt);
;             if constexpr (SP2) {
;             PG8_LDB(B0, 0, 0); PG8_LDB(B1, 0, 1); PG8_SCHED; PG8_LDA(At, 0, 0); PG8_STAGE(PG8_SA(1, 1), a1 + hstep, voffA);
;             PG8_WAIT_V(8); PG8_WAIT_L(0); PG8_BAR; PG8_MMA(0, 0, At, B0); PG8_MMA(0, 1, At, B1); PG8_BAR; PG8_SCHED;
;             PG8_LDA(At, 0, 1); PG8_STAGE(PG8_SB(0, 0), b2, voffB); PG8_STAGE(PG8_SB(0, 1), b2 + hstep, voffB); PG8_STAGE(PG8_SA(0, 0), a2, voffA);
;             PG8_WAIT_V(8); PG8_WAIT_L(0); PG8_BAR; PG8_MMA(1, 0, At, B0); PG8_MMA(1, 1, At, B1); PG8_BAR; PG8_SCHED;
.LBB0_700:
	ds_read_b128 v[164:167], v155
	ds_read_b128 v[168:171], v155 offset:1024
	ds_read_b128 v[172:175], v155 offset:2048
	ds_read_b128 v[176:179], v155 offset:3072
	ds_read_b128 v[180:183], v157
	ds_read_b128 v[184:187], v157 offset:1024
	ds_read_b128 v[188:191], v157 offset:2048
	ds_read_b128 v[192:195], v157 offset:3072
	s_add_u32 s46, s44, 0xfff80080
	s_addc_u32 s47, s45, -1
	s_cmp_eq_u32 s67, 28
	s_cselect_b32 s49, s10, s47
	s_cselect_b32 s48, s11, s46
	s_cselect_b32 s47, s21, s66
	s_cselect_b32 s46, s37, s65
	v_lshl_add_u64 v[228:229], s[44:45], 0, v[138:139]
	s_add_i32 m0, s43, 0xc000
	ds_read_b128 v[196:199], v159
	ds_read_b128 v[200:203], v159 offset:1024
	ds_read_b128 v[204:207], v159 offset:2048
	ds_read_b128 v[208:211], v159 offset:3072
	ds_read_b128 v[212:215], v159 offset:4096
	ds_read_b128 v[216:219], v159 offset:5120
	ds_read_b128 v[220:223], v159 offset:6144
	ds_read_b128 v[224:227], v159 offset:7168
	global_load_lds_dwordx4 v[228:229], off
	v_lshl_add_u64 v[228:229], s[44:45], 0, v[140:141]
	s_add_i32 m0, s43, 0xe000
	s_nop 0
	global_load_lds_dwordx4 v[228:229], off
	s_waitcnt vmcnt(8)
	s_waitcnt lgkmcnt(0)
	s_barrier
	s_setprio 1
	s_waitcnt lgkmcnt(0)
	v_mfma_f32_16x16x32_bf16 v[124:127], v[164:167], v[196:199], v[124:127]
	v_mfma_f32_16x16x32_bf16 v[124:127], v[168:171], v[200:203], v[124:127]
	v_mfma_f32_16x16x32_bf16 v[120:123], v[172:175], v[196:199], v[120:123]
	v_mfma_f32_16x16x32_bf16 v[120:123], v[176:179], v[200:203], v[120:123]
	v_mfma_f32_16x16x32_bf16 v[104:107], v[172:175], v[204:207], v[104:107]
	v_mfma_f32_16x16x32_bf16 v[104:107], v[176:179], v[208:211], v[104:107]
	v_mfma_f32_16x16x32_bf16 v[108:111], v[164:167], v[204:207], v[108:111]
	v_mfma_f32_16x16x32_bf16 v[108:111], v[168:171], v[208:211], v[108:111]
	v_mfma_f32_16x16x32_bf16 v[92:95], v[164:167], v[212:215], v[92:95]
	v_mfma_f32_16x16x32_bf16 v[92:95], v[168:171], v[216:219], v[92:95]
	v_mfma_f32_16x16x32_bf16 v[88:91], v[172:175], v[212:215], v[88:91]
	v_mfma_f32_16x16x32_bf16 v[88:91], v[176:179], v[216:219], v[88:91]
	v_mfma_f32_16x16x32_bf16 v[72:75], v[172:175], v[220:223], v[72:75]
	v_mfma_f32_16x16x32_bf16 v[72:75], v[176:179], v[224:227], v[72:75]
	v_mfma_f32_16x16x32_bf16 v[76:79], v[164:167], v[220:223], v[76:79]
	v_mfma_f32_16x16x32_bf16 v[76:79], v[168:171], v[224:227], v[76:79]
	s_setprio 0
	s_setprio 1
	v_mfma_f32_16x16x32_bf16 v[116:119], v[180:183], v[196:199], v[116:119]
	v_mfma_f32_16x16x32_bf16 v[116:119], v[184:187], v[200:203], v[116:119]
	v_mfma_f32_16x16x32_bf16 v[112:115], v[188:191], v[196:199], v[112:115]
	v_mfma_f32_16x16x32_bf16 v[112:115], v[192:195], v[200:203], v[112:115]
	v_mfma_f32_16x16x32_bf16 v[96:99], v[188:191], v[204:207], v[96:99]
	v_mfma_f32_16x16x32_bf16 v[96:99], v[192:195], v[208:211], v[96:99]
	v_mfma_f32_16x16x32_bf16 v[100:103], v[180:183], v[204:207], v[100:103]
	v_mfma_f32_16x16x32_bf16 v[100:103], v[184:187], v[208:211], v[100:103]
	v_mfma_f32_16x16x32_bf16 v[84:87], v[180:183], v[212:215], v[84:87]
	v_mfma_f32_16x16x32_bf16 v[84:87], v[184:187], v[216:219], v[84:87]
	v_mfma_f32_16x16x32_bf16 v[80:83], v[188:191], v[212:215], v[80:83]
	v_mfma_f32_16x16x32_bf16 v[80:83], v[192:195], v[216:219], v[80:83]
	v_mfma_f32_16x16x32_bf16 v[64:67], v[188:191], v[220:223], v[64:67]
	v_mfma_f32_16x16x32_bf16 v[64:67], v[192:195], v[224:227], v[64:67]
	v_mfma_f32_16x16x32_bf16 v[68:71], v[180:183], v[220:223], v[68:71]
	v_mfma_f32_16x16x32_bf16 v[68:71], v[184:187], v[224:227], v[68:71]
	s_setprio 0
	s_barrier
	s_add_i32 s62, s58, s3
	v_lshl_add_u64 v[228:229], s[46:47], 0, v[130:131]
	s_mov_b32 m0, s62
	ds_read_b128 v[196:199], v159 offset:16384
	ds_read_b128 v[200:203], v159 offset:17408
	ds_read_b128 v[204:207], v159 offset:18432
	ds_read_b128 v[208:211], v159 offset:19456
	ds_read_b128 v[212:215], v159 offset:20480
	ds_read_b128 v[216:219], v159 offset:21504
	ds_read_b128 v[220:223], v159 offset:22528
	ds_read_b128 v[224:227], v159 offset:23552
	global_load_lds_dwordx4 v[228:229], off
	s_add_i32 m0, s62, 0x2000
	s_add_u32 s62, s46, 0x80000
	v_lshl_add_u64 v[230:231], s[46:47], 0, v[134:135]
	s_addc_u32 s63, s47, 0
	s_add_i32 s68, s59, s3
	global_load_lds_dwordx4 v[230:231], off
	v_lshl_add_u64 v[232:233], s[62:63], 0, v[130:131]
	s_mov_b32 m0, s68
	v_lshl_add_u64 v[234:235], s[48:49], 0, v[132:133]
	global_load_lds_dwordx4 v[232:233], off
	v_lshl_add_u64 v[232:233], s[62:63], 0, v[134:135]
	s_add_i32 m0, s68, 0x2000
	s_nop 0
	global_load_lds_dwordx4 v[232:233], off
	v_lshl_add_u64 v[232:233], s[48:49], 0, v[128:129]
	s_mov_b32 m0, s43
	s_nop 0
	global_load_lds_dwordx4 v[232:233], off
	s_mov_b32 m0, s50
	s_nop 0
	global_load_lds_dwordx4 v[234:235], off
	s_waitcnt vmcnt(8)
	s_waitcnt lgkmcnt(0)
	s_barrier
; #define PG8_STAGE(bufoff, gbase, voff) do { _Pragma("unroll") for (int _i = 0; _i < 2; ++_i) \
;         __builtin_amdgcn_global_load_lds((const unsigned*)((const char*)(gbase) + (voff)[_i]), (PG8_LAS unsigned*)(lds + (bufoff) + ldsw + _i * 8192), 16, 0, 0); } while (0)
; #define PG8_LDA(dst, b, h) do { _Pragma("unroll") for (int m = 0; m < 4; ++m) _Pragma("unroll") for (int k = 0; k < 2; ++k) dst[m][k] = *(const PG8_LAS bf16x8*)(lds + PG8_SA(b, h) + aoff + m * 2048 + k * 1024); } while (0)
; #define PG8_LDB(dst, b, h) do { _Pragma("unroll") for (int n = 0; n < 2; ++n) _Pragma("unroll") for (int k = 0; k < 2; ++k) dst[n][k] = *(const PG8_LAS bf16x8*)(lds + PG8_SB(b, h) + boff + n * 2048 + k * 1024); } while (0)
; #define PG8_MMA(ai, bj, At, Bt) do { __builtin_amdgcn_s_setprio(1); _Pragma("unroll") for (int m = 0; m < 4; ++m) _Pragma("unroll") for (int n = 0; n < 2; ++n) _Pragma("unroll") for (int k = 0; k < 2; ++k) \
;         acc[ai][bj][m][n] = __builtin_amdgcn_mfma_f32_16x16x32_bf16(Bt[n][k], At[m][k], acc[ai][bj][m][n], 0, 0, 0); __builtin_amdgcn_s_setprio(0); } while (0)
; #define PG8_WAIT_V(n) asm volatile("s_waitcnt vmcnt(" #n ")" ::: "memory")
; #define PG8_WAIT_L(n) asm volatile("s_waitcnt lgkmcnt(" #n ")" ::: "memory")
; #define PG8_BAR __builtin_amdgcn_s_barrier()
; #define PG8_SCHED __builtin_amdgcn_sched_barrier(0)
; template <class Epi, class Sched, bool ALIGN_EPI = false, bool SP2 = false>
; __device__ __forceinline__ void gemm_phase(PG8_LAS unsigned char* lds, const Gemm g, const Sched& S, const Epi& E) {
;     ...
;             PG8_WAIT_V(8); PG8_WAIT_L(0); PG8_BAR; PG8_MMA(1, 0, At, B0); PG8_MMA(1, 1, At, B1); PG8_BAR; PG8_SCHED;
;             PG8_LDB(B0, 1, 0); PG8_LDB(B1, 1, 1); PG8_SCHED; PG8_LDA(At, 1, 0); PG8_STAGE(PG8_SA(0, 1), a2 + hstep, voffA);
;             PG8_WAIT_V(8); PG8_WAIT_L(0); PG8_BAR; PG8_MMA(0, 0, At, B0); PG8_MMA(0, 1, At, B1); PG8_BAR; PG8_SCHED;
	s_setprio 1
	s_waitcnt lgkmcnt(0)
	v_mfma_f32_16x16x32_bf16 v[60:63], v[164:167], v[196:199], v[60:63]
	v_mfma_f32_16x16x32_bf16 v[60:63], v[168:171], v[200:203], v[60:63]
	v_mfma_f32_16x16x32_bf16 v[56:59], v[172:175], v[196:199], v[56:59]
	v_mfma_f32_16x16x32_bf16 v[56:59], v[176:179], v[200:203], v[56:59]
	v_mfma_f32_16x16x32_bf16 v[40:43], v[172:175], v[204:207], v[40:43]
	v_mfma_f32_16x16x32_bf16 v[40:43], v[176:179], v[208:211], v[40:43]
	v_mfma_f32_16x16x32_bf16 v[44:47], v[164:167], v[204:207], v[44:47]
	v_mfma_f32_16x16x32_bf16 v[44:47], v[168:171], v[208:211], v[44:47]
	v_mfma_f32_16x16x32_bf16 v[28:31], v[164:167], v[212:215], v[28:31]
	v_mfma_f32_16x16x32_bf16 v[28:31], v[168:171], v[216:219], v[28:31]
	v_mfma_f32_16x16x32_bf16 v[24:27], v[172:175], v[212:215], v[24:27]
	v_mfma_f32_16x16x32_bf16 v[24:27], v[176:179], v[216:219], v[24:27]
	v_mfma_f32_16x16x32_bf16 v[8:11], v[172:175], v[220:223], v[8:11]
	v_mfma_f32_16x16x32_bf16 v[8:11], v[176:179], v[224:227], v[8:11]
	v_mfma_f32_16x16x32_bf16 v[12:15], v[164:167], v[220:223], v[12:15]
	v_mfma_f32_16x16x32_bf16 v[12:15], v[168:171], v[224:227], v[12:15]
	s_setprio 0
	s_setprio 1
	v_mfma_f32_16x16x32_bf16 v[52:55], v[180:183], v[196:199], v[52:55]
	v_mfma_f32_16x16x32_bf16 v[52:55], v[184:187], v[200:203], v[52:55]
	v_mfma_f32_16x16x32_bf16 v[48:51], v[188:191], v[196:199], v[48:51]
	v_mfma_f32_16x16x32_bf16 v[48:51], v[192:195], v[200:203], v[48:51]
	v_mfma_f32_16x16x32_bf16 v[32:35], v[188:191], v[204:207], v[32:35]
	v_mfma_f32_16x16x32_bf16 v[32:35], v[192:195], v[208:211], v[32:35]
	v_mfma_f32_16x16x32_bf16 v[36:39], v[180:183], v[204:207], v[36:39]
	v_mfma_f32_16x16x32_bf16 v[36:39], v[184:187], v[208:211], v[36:39]
	v_mfma_f32_16x16x32_bf16 v[20:23], v[180:183], v[212:215], v[20:23]
	v_mfma_f32_16x16x32_bf16 v[20:23], v[184:187], v[216:219], v[20:23]
	v_mfma_f32_16x16x32_bf16 v[16:19], v[188:191], v[212:215], v[16:19]
	v_mfma_f32_16x16x32_bf16 v[16:19], v[192:195], v[216:219], v[16:19]
	v_mfma_f32_16x16x32_bf16 v[0:3], v[188:191], v[220:223], v[0:3]
	v_mfma_f32_16x16x32_bf16 v[0:3], v[192:195], v[224:227], v[0:3]
	v_mfma_f32_16x16x32_bf16 v[4:7], v[180:183], v[220:223], v[4:7]
	v_mfma_f32_16x16x32_bf16 v[4:7], v[184:187], v[224:227], v[4:7]
	s_setprio 0
	s_barrier
	s_add_i32 s62, 0, 0x18000
	v_add_u32_e32 v161, s62, v147
	s_add_i32 s63, 0, 0x1c000
	ds_read_b128 v[164:167], v161
	ds_read_b128 v[168:171], v161 offset:1024
	ds_read_b128 v[172:175], v161 offset:2048
	ds_read_b128 v[176:179], v161 offset:3072
	v_add_u32_e32 v161, s63, v147
	ds_read_b128 v[180:183], v161
	ds_read_b128 v[184:187], v161 offset:1024
	ds_read_b128 v[188:191], v161 offset:2048
	ds_read_b128 v[192:195], v161 offset:3072
	s_add_u32 s48, s48, 0x80000
	s_addc_u32 s49, s49, 0
	s_mov_b32 m0, s51
	v_lshl_add_u64 v[236:237], s[48:49], 0, v[128:129]
	ds_read_b128 v[196:199], v159 offset:32768
	ds_read_b128 v[200:203], v159 offset:33792
	ds_read_b128 v[204:207], v159 offset:34816
	ds_read_b128 v[208:211], v159 offset:35840
	ds_read_b128 v[212:215], v159 offset:36864
	ds_read_b128 v[216:219], v159 offset:37888
	ds_read_b128 v[220:223], v159 offset:38912
	ds_read_b128 v[224:227], v159 offset:39936
	global_load_lds_dwordx4 v[236:237], off
	v_lshl_add_u64 v[236:237], s[48:49], 0, v[132:133]
	s_mov_b32 m0, s52
	s_nop 0
	global_load_lds_dwordx4 v[236:237], off
	s_waitcnt vmcnt(8)
	s_waitcnt lgkmcnt(0)
	s_barrier
	s_setprio 1
	s_waitcnt lgkmcnt(0)
	v_mfma_f32_16x16x32_bf16 v[124:127], v[164:167], v[196:199], v[124:127]
	v_mfma_f32_16x16x32_bf16 v[124:127], v[168:171], v[200:203], v[124:127]
	v_mfma_f32_16x16x32_bf16 v[120:123], v[172:175], v[196:199], v[120:123]
	v_mfma_f32_16x16x32_bf16 v[120:123], v[176:179], v[200:203], v[120:123]
	v_mfma_f32_16x16x32_bf16 v[104:107], v[172:175], v[204:207], v[104:107]
	v_mfma_f32_16x16x32_bf16 v[104:107], v[176:179], v[208:211], v[104:107]
	v_mfma_f32_16x16x32_bf16 v[108:111], v[164:167], v[204:207], v[108:111]
	v_mfma_f32_16x16x32_bf16 v[108:111], v[168:171], v[208:211], v[108:111]
	v_mfma_f32_16x16x32_bf16 v[92:95], v[164:167], v[212:215], v[92:95]
	v_mfma_f32_16x16x32_bf16 v[92:95], v[168:171], v[216:219], v[92:95]
	v_mfma_f32_16x16x32_bf16 v[88:91], v[172:175], v[212:215], v[88:91]
	v_mfma_f32_16x16x32_bf16 v[88:91], v[176:179], v[216:219], v[88:91]
	v_mfma_f32_16x16x32_bf16 v[72:75], v[172:175], v[220:223], v[72:75]
	v_mfma_f32_16x16x32_bf16 v[72:75], v[176:179], v[224:227], v[72:75]
	v_mfma_f32_16x16x32_bf16 v[76:79], v[164:167], v[220:223], v[76:79]
	v_mfma_f32_16x16x32_bf16 v[76:79], v[168:171], v[224:227], v[76:79]
	s_setprio 0
	s_setprio 1
	v_mfma_f32_16x16x32_bf16 v[116:119], v[180:183], v[196:199], v[116:119]
	v_mfma_f32_16x16x32_bf16 v[116:119], v[184:187], v[200:203], v[116:119]
	v_mfma_f32_16x16x32_bf16 v[112:115], v[188:191], v[196:199], v[112:115]
	v_mfma_f32_16x16x32_bf16 v[112:115], v[192:195], v[200:203], v[112:115]
	v_mfma_f32_16x16x32_bf16 v[96:99], v[188:191], v[204:207], v[96:99]
	v_mfma_f32_16x16x32_bf16 v[96:99], v[192:195], v[208:211], v[96:99]
	v_mfma_f32_16x16x32_bf16 v[100:103], v[180:183], v[204:207], v[100:103]
	v_mfma_f32_16x16x32_bf16 v[100:103], v[184:187], v[208:211], v[100:103]
	v_mfma_f32_16x16x32_bf16 v[84:87], v[180:183], v[212:215], v[84:87]
	v_mfma_f32_16x16x32_bf16 v[84:87], v[184:187], v[216:219], v[84:87]
	v_mfma_f32_16x16x32_bf16 v[80:83], v[188:191], v[212:215], v[80:83]
	v_mfma_f32_16x16x32_bf16 v[80:83], v[192:195], v[216:219], v[80:83]
	v_mfma_f32_16x16x32_bf16 v[64:67], v[188:191], v[220:223], v[64:67]
	v_mfma_f32_16x16x32_bf16 v[64:67], v[192:195], v[224:227], v[64:67]
	v_mfma_f32_16x16x32_bf16 v[68:71], v[180:183], v[220:223], v[68:71]
	v_mfma_f32_16x16x32_bf16 v[68:71], v[184:187], v[224:227], v[68:71]
	s_setprio 0
	s_barrier
; #define PG8_STAGE(bufoff, gbase, voff) do { _Pragma("unroll") for (int _i = 0; _i < 2; ++_i) \
;         __builtin_amdgcn_global_load_lds((const unsigned*)((const char*)(gbase) + (voff)[_i]), (PG8_LAS unsigned*)(lds + (bufoff) + ldsw + _i * 8192), 16, 0, 0); } while (0)
; #define PG8_LDA(dst, b, h) do { _Pragma("unroll") for (int m = 0; m < 4; ++m) _Pragma("unroll") for (int k = 0; k < 2; ++k) dst[m][k] = *(const PG8_LAS bf16x8*)(lds + PG8_SA(b, h) + aoff + m * 2048 + k * 1024); } while (0)
; #define PG8_MMA(ai, bj, At, Bt) do { __builtin_amdgcn_s_setprio(1); _Pragma("unroll") for (int m = 0; m < 4; ++m) _Pragma("unroll") for (int n = 0; n < 2; ++n) _Pragma("unroll") for (int k = 0; k < 2; ++k) \
;         acc[ai][bj][m][n] = __builtin_amdgcn_mfma_f32_16x16x32_bf16(Bt[n][k], At[m][k], acc[ai][bj][m][n], 0, 0, 0); __builtin_amdgcn_s_setprio(0); } while (0)
; #define PG8_WAIT_V(n) asm volatile("s_waitcnt vmcnt(" #n ")" ::: "memory")
; #define PG8_WAIT_L(n) asm volatile("s_waitcnt lgkmcnt(" #n ")" ::: "memory")
; #define PG8_BAR __builtin_amdgcn_s_barrier()
; #define PG8_SCHED __builtin_amdgcn_sched_barrier(0)
; template <class Epi, class Sched, bool ALIGN_EPI = false, bool SP2 = false>
; __device__ __forceinline__ void gemm_phase(PG8_LAS unsigned char* lds, const Gemm g, const Sched& S, const Epi& E) {
;     ...
;             PG8_LDA(At, 1, 1); PG8_STAGE(PG8_SB(1, 0), b3, voffB); PG8_STAGE(PG8_SB(1, 1), b3 + hstep, voffB); PG8_STAGE(PG8_SA(1, 0), a3, voffA);
;             PG8_WAIT_V(8); PG8_WAIT_L(0); PG8_BAR; PG8_MMA(1, 0, At, B0); PG8_MMA(1, 1, At, B1); PG8_BAR; PG8_SCHED;
;     ...
;         if constexpr (ALIGN_EPI) { if (wr == 0) PG8_BAR; }
	s_add_i32 s48, s62, s3
	v_lshl_add_u64 v[228:229], v[228:229], 0, s[8:9]
	s_mov_b32 m0, s48
	ds_read_b128 v[196:199], v159 offset:49152
	ds_read_b128 v[200:203], v159 offset:50176
	ds_read_b128 v[204:207], v159 offset:51200
	ds_read_b128 v[208:211], v159 offset:52224
	ds_read_b128 v[212:215], v159 offset:53248
	ds_read_b128 v[216:219], v159 offset:54272
	ds_read_b128 v[220:223], v159 offset:55296
	ds_read_b128 v[224:227], v159 offset:56320
	global_load_lds_dwordx4 v[228:229], off
	s_add_i32 m0, s48, 0x2000
	s_add_u32 s46, s46, 0x80080
	v_lshl_add_u64 v[228:229], v[230:231], 0, s[8:9]
	s_addc_u32 s47, s47, 0
	s_add_i32 s48, s63, s3
	global_load_lds_dwordx4 v[228:229], off
	v_lshl_add_u64 v[228:229], s[46:47], 0, v[130:131]
	s_mov_b32 m0, s48
	s_nop 0
	global_load_lds_dwordx4 v[228:229], off
	v_lshl_add_u64 v[228:229], s[46:47], 0, v[134:135]
	s_add_i32 m0, s48, 0x2000
	s_nop 0
	global_load_lds_dwordx4 v[228:229], off
	v_lshl_add_u64 v[228:229], v[232:233], 0, s[8:9]
	s_mov_b32 m0, s55
	s_nop 0
	global_load_lds_dwordx4 v[228:229], off
	v_lshl_add_u64 v[228:229], v[234:235], 0, s[8:9]
	s_mov_b32 m0, s56
	s_nop 0
	global_load_lds_dwordx4 v[228:229], off
	s_waitcnt vmcnt(8)
	s_waitcnt lgkmcnt(0)
	s_barrier
	s_setprio 1
	s_waitcnt lgkmcnt(0)
	v_mfma_f32_16x16x32_bf16 v[60:63], v[164:167], v[196:199], v[60:63]
	v_mfma_f32_16x16x32_bf16 v[60:63], v[168:171], v[200:203], v[60:63]
	v_mfma_f32_16x16x32_bf16 v[56:59], v[172:175], v[196:199], v[56:59]
	v_mfma_f32_16x16x32_bf16 v[56:59], v[176:179], v[200:203], v[56:59]
	v_mfma_f32_16x16x32_bf16 v[40:43], v[172:175], v[204:207], v[40:43]
	v_mfma_f32_16x16x32_bf16 v[40:43], v[176:179], v[208:211], v[40:43]
	v_mfma_f32_16x16x32_bf16 v[44:47], v[164:167], v[204:207], v[44:47]
	v_mfma_f32_16x16x32_bf16 v[44:47], v[168:171], v[208:211], v[44:47]
	v_mfma_f32_16x16x32_bf16 v[28:31], v[164:167], v[212:215], v[28:31]
	v_mfma_f32_16x16x32_bf16 v[28:31], v[168:171], v[216:219], v[28:31]
	v_mfma_f32_16x16x32_bf16 v[24:27], v[172:175], v[212:215], v[24:27]
	v_mfma_f32_16x16x32_bf16 v[24:27], v[176:179], v[216:219], v[24:27]
	v_mfma_f32_16x16x32_bf16 v[8:11], v[172:175], v[220:223], v[8:11]
	v_mfma_f32_16x16x32_bf16 v[8:11], v[176:179], v[224:227], v[8:11]
	v_mfma_f32_16x16x32_bf16 v[12:15], v[164:167], v[220:223], v[12:15]
	v_mfma_f32_16x16x32_bf16 v[12:15], v[168:171], v[224:227], v[12:15]
	s_setprio 0
	s_setprio 1
	v_mfma_f32_16x16x32_bf16 v[52:55], v[180:183], v[196:199], v[52:55]
	v_mfma_f32_16x16x32_bf16 v[52:55], v[184:187], v[200:203], v[52:55]
	v_mfma_f32_16x16x32_bf16 v[48:51], v[188:191], v[196:199], v[48:51]
	v_mfma_f32_16x16x32_bf16 v[48:51], v[192:195], v[200:203], v[48:51]
	v_mfma_f32_16x16x32_bf16 v[32:35], v[188:191], v[204:207], v[32:35]
	v_mfma_f32_16x16x32_bf16 v[32:35], v[192:195], v[208:211], v[32:35]
	v_mfma_f32_16x16x32_bf16 v[36:39], v[180:183], v[204:207], v[36:39]
	v_mfma_f32_16x16x32_bf16 v[36:39], v[184:187], v[208:211], v[36:39]
	v_mfma_f32_16x16x32_bf16 v[20:23], v[180:183], v[212:215], v[20:23]
	v_mfma_f32_16x16x32_bf16 v[20:23], v[184:187], v[216:219], v[20:23]
	v_mfma_f32_16x16x32_bf16 v[16:19], v[188:191], v[212:215], v[16:19]
	v_mfma_f32_16x16x32_bf16 v[16:19], v[192:195], v[216:219], v[16:19]
	v_mfma_f32_16x16x32_bf16 v[0:3], v[188:191], v[220:223], v[0:3]
	v_mfma_f32_16x16x32_bf16 v[0:3], v[192:195], v[224:227], v[0:3]
	v_mfma_f32_16x16x32_bf16 v[4:7], v[180:183], v[220:223], v[4:7]
	v_mfma_f32_16x16x32_bf16 v[4:7], v[184:187], v[224:227], v[4:7]
	s_setprio 0
	s_barrier
	s_add_i32 s67, s67, 2
	s_add_u32 s44, s44, 0x100
	s_addc_u32 s45, s45, 0
	s_add_u32 s65, s65, 0x100
	s_addc_u32 s66, s66, 0
	s_cmp_gt_u32 s67, 29
	s_cbranch_scc0 .LBB0_700
	s_and_b64 vcc, exec, s[12:13]
	s_cbranch_vccz .LBB0_703
	s_barrier

; #define PG8_STAGE(bufoff, gbase, voff) do { _Pragma("unroll") for (int _i = 0; _i < 2; ++_i) \
;         __builtin_amdgcn_global_load_lds((const unsigned*)((const char*)(gbase) + (voff)[_i]), (PG8_LAS unsigned*)(lds + (bufoff) + ldsw + _i * 8192), 16, 0, 0); } while (0)
; #define PG8_LDA(dst, b, h) do { _Pragma("unroll") for (int m = 0; m < 4; ++m) _Pragma("unroll") for (int k = 0; k < 2; ++k) dst[m][k] = *(const PG8_LAS bf16x8*)(lds + PG8_SA(b, h) + aoff + m * 2048 + k * 1024); } while (0)
; #define PG8_LDB(dst, b, h) do { _Pragma("unroll") for (int n = 0; n < 2; ++n) _Pragma("unroll") for (int k = 0; k < 2; ++k) dst[n][k] = *(const PG8_LAS bf16x8*)(lds + PG8_SB(b, h) + boff + n * 2048 + k * 1024); } while (0)
; #define PG8_MMA(ai, bj, At, Bt) do { __builtin_amdgcn_s_setprio(1); _Pragma("unroll") for (int m = 0; m < 4; ++m) _Pragma("unroll") for (int n = 0; n < 2; ++n) _Pragma("unroll") for (int k = 0; k < 2; ++k) \
;         acc[ai][bj][m][n] = __builtin_amdgcn_mfma_f32_16x16x32_bf16(Bt[n][k], At[m][k], acc[ai][bj][m][n], 0, 0, 0); __builtin_amdgcn_s_setprio(0); } while (0)
; #define PG8_WAIT_V(n) asm volatile("s_waitcnt vmcnt(" #n ")" ::: "memory")
; #define PG8_WAIT_L(n) asm volatile("s_waitcnt lgkmcnt(" #n ")" ::: "memory")
; template <class Epi, class Sched, bool ALIGN_EPI = false, bool SP2 = false>
; __device__ __forceinline__ void gemm_phase(PG8_LAS unsigned char* lds, const Gemm g, const Sched& S, const Epi& E) {
;     ...
;             const bool last = (t == nt - 2);
;             const char* a1 = cA + (size_t)(t + 1) * kstep;
;             const char* a2 = last ? nA : cA + (size_t)(t + 2) * kstep; const char* b2 = last ? nB : cB + (size_t)(t + 2) * kstep;
;             const char* a3 = a2 + kstep; const char* b3 = b2 + kstep;
;             if (last && has_next) S.a_ready(nxt);
;             if constexpr (SP2) {
;             PG8_LDB(B0, 0, 0); PG8_LDB(B1, 0, 1); PG8_SCHED; PG8_LDA(At, 0, 0); PG8_STAGE(PG8_SA(1, 1), a1 + hstep, voffA);
;             PG8_WAIT_V(8); PG8_WAIT_L(0); PG8_BAR; PG8_MMA(0, 0, At, B0); PG8_MMA(0, 1, At, B1); PG8_BAR; PG8_SCHED;
;             PG8_LDA(At, 0, 1); PG8_STAGE(PG8_SB(0, 0), b2, voffB); PG8_STAGE(PG8_SB(0, 1), b2 + hstep, voffB); PG8_STAGE(PG8_SA(0, 0), a2, voffA);
;             PG8_WAIT_V(8); PG8_WAIT_L(0); PG8_BAR; PG8_MMA(1, 0, At, B0); PG8_MMA(1, 1, At, B1); PG8_BAR; PG8_SCHED;
.LBB0_779:
	ds_read_b128 v[144:147], v155
	ds_read_b128 v[160:163], v155 offset:1024
	ds_read_b128 v[164:167], v155 offset:2048
	ds_read_b128 v[168:171], v155 offset:3072
	ds_read_b128 v[172:175], v156
	ds_read_b128 v[176:179], v156 offset:1024
	ds_read_b128 v[180:183], v156 offset:2048
	ds_read_b128 v[184:187], v156 offset:3072
	s_add_u32 s40, s38, 0xffea0080
	s_addc_u32 s41, s39, -1
	s_cmpk_eq_i32 s58, 0x54
	s_cselect_b32 s43, s7, s41
	s_cselect_b32 s42, s6, s40
	s_cselect_b32 s41, s37, s57
	s_cselect_b32 s40, s36, s11
	v_lshl_add_u64 v[220:221], s[38:39], 0, v[136:137]
	s_add_i32 m0, s33, 0xc000
	ds_read_b128 v[188:191], v157
	ds_read_b128 v[192:195], v157 offset:1024
	ds_read_b128 v[196:199], v157 offset:2048
	ds_read_b128 v[200:203], v157 offset:3072
	ds_read_b128 v[204:207], v157 offset:4096
	ds_read_b128 v[208:211], v157 offset:5120
	ds_read_b128 v[212:215], v157 offset:6144
	ds_read_b128 v[216:219], v157 offset:7168
	global_load_lds_dwordx4 v[220:221], off
	v_lshl_add_u64 v[220:221], s[38:39], 0, v[138:139]
	s_add_i32 m0, s33, 0xe000
	s_nop 0
	global_load_lds_dwordx4 v[220:221], off
	s_waitcnt vmcnt(8)
	s_waitcnt lgkmcnt(0)
	s_barrier
	s_setprio 1
	s_waitcnt lgkmcnt(0)
	v_mfma_f32_16x16x32_bf16 v[124:127], v[144:147], v[188:191], v[124:127]
	v_mfma_f32_16x16x32_bf16 v[124:127], v[160:163], v[192:195], v[124:127]
	v_mfma_f32_16x16x32_bf16 v[120:123], v[164:167], v[188:191], v[120:123]
	v_mfma_f32_16x16x32_bf16 v[120:123], v[168:171], v[192:195], v[120:123]
	v_mfma_f32_16x16x32_bf16 v[104:107], v[164:167], v[196:199], v[104:107]
	v_mfma_f32_16x16x32_bf16 v[104:107], v[168:171], v[200:203], v[104:107]
	v_mfma_f32_16x16x32_bf16 v[108:111], v[144:147], v[196:199], v[108:111]
	v_mfma_f32_16x16x32_bf16 v[108:111], v[160:163], v[200:203], v[108:111]
	v_mfma_f32_16x16x32_bf16 v[92:95], v[144:147], v[204:207], v[92:95]
	v_mfma_f32_16x16x32_bf16 v[92:95], v[160:163], v[208:211], v[92:95]
	v_mfma_f32_16x16x32_bf16 v[88:91], v[164:167], v[204:207], v[88:91]
	v_mfma_f32_16x16x32_bf16 v[88:91], v[168:171], v[208:211], v[88:91]
	v_mfma_f32_16x16x32_bf16 v[72:75], v[164:167], v[212:215], v[72:75]
	v_mfma_f32_16x16x32_bf16 v[72:75], v[168:171], v[216:219], v[72:75]
	v_mfma_f32_16x16x32_bf16 v[76:79], v[144:147], v[212:215], v[76:79]
	v_mfma_f32_16x16x32_bf16 v[76:79], v[160:163], v[216:219], v[76:79]
	s_setprio 0
	s_setprio 1
	v_mfma_f32_16x16x32_bf16 v[116:119], v[172:175], v[188:191], v[116:119]
	v_mfma_f32_16x16x32_bf16 v[116:119], v[176:179], v[192:195], v[116:119]
	v_mfma_f32_16x16x32_bf16 v[112:115], v[180:183], v[188:191], v[112:115]
	v_mfma_f32_16x16x32_bf16 v[112:115], v[184:187], v[192:195], v[112:115]
	v_mfma_f32_16x16x32_bf16 v[96:99], v[180:183], v[196:199], v[96:99]
	v_mfma_f32_16x16x32_bf16 v[96:99], v[184:187], v[200:203], v[96:99]
	v_mfma_f32_16x16x32_bf16 v[100:103], v[172:175], v[196:199], v[100:103]
	v_mfma_f32_16x16x32_bf16 v[100:103], v[176:179], v[200:203], v[100:103]
	v_mfma_f32_16x16x32_bf16 v[84:87], v[172:175], v[204:207], v[84:87]
	v_mfma_f32_16x16x32_bf16 v[84:87], v[176:179], v[208:211], v[84:87]
	v_mfma_f32_16x16x32_bf16 v[80:83], v[180:183], v[204:207], v[80:83]
	v_mfma_f32_16x16x32_bf16 v[80:83], v[184:187], v[208:211], v[80:83]
	v_mfma_f32_16x16x32_bf16 v[64:67], v[180:183], v[212:215], v[64:67]
	v_mfma_f32_16x16x32_bf16 v[64:67], v[184:187], v[216:219], v[64:67]
	v_mfma_f32_16x16x32_bf16 v[68:71], v[172:175], v[212:215], v[68:71]
	v_mfma_f32_16x16x32_bf16 v[68:71], v[176:179], v[216:219], v[68:71]
	s_setprio 0
	s_barrier
	s_add_i32 s59, s52, s3
	v_lshl_add_u64 v[220:221], s[40:41], 0, v[130:131]
	s_mov_b32 m0, s59
	ds_read_b128 v[188:191], v157 offset:16384
	ds_read_b128 v[192:195], v157 offset:17408
	ds_read_b128 v[196:199], v157 offset:18432
	ds_read_b128 v[200:203], v157 offset:19456
	ds_read_b128 v[204:207], v157 offset:20480
	ds_read_b128 v[208:211], v157 offset:21504
	ds_read_b128 v[212:215], v157 offset:22528
	ds_read_b128 v[216:219], v157 offset:23552
	global_load_lds_dwordx4 v[220:221], off
	s_add_i32 m0, s59, 0x2000
	s_add_u32 s62, s40, 0x160000
	v_lshl_add_u64 v[222:223], s[40:41], 0, v[134:135]
	s_addc_u32 s63, s41, 0
	s_add_i32 s59, s53, s3
	global_load_lds_dwordx4 v[222:223], off
	v_lshl_add_u64 v[224:225], s[62:63], 0, v[130:131]
	s_mov_b32 m0, s59
	v_lshl_add_u64 v[226:227], s[42:43], 0, v[132:133]
	global_load_lds_dwordx4 v[224:225], off
	v_lshl_add_u64 v[224:225], s[62:63], 0, v[134:135]
	s_add_i32 m0, s59, 0x2000
	s_nop 0
	global_load_lds_dwordx4 v[224:225], off
	v_lshl_add_u64 v[224:225], s[42:43], 0, v[128:129]
	s_mov_b32 m0, s33
	s_nop 0
	global_load_lds_dwordx4 v[224:225], off
	s_mov_b32 m0, s35
	s_nop 0
	global_load_lds_dwordx4 v[226:227], off
	s_waitcnt vmcnt(8)
	s_waitcnt lgkmcnt(0)
	s_barrier
; #define PG8_STAGE(bufoff, gbase, voff) do { _Pragma("unroll") for (int _i = 0; _i < 2; ++_i) \
;         __builtin_amdgcn_global_load_lds((const unsigned*)((const char*)(gbase) + (voff)[_i]), (PG8_LAS unsigned*)(lds + (bufoff) + ldsw + _i * 8192), 16, 0, 0); } while (0)
; #define PG8_LDA(dst, b, h) do { _Pragma("unroll") for (int m = 0; m < 4; ++m) _Pragma("unroll") for (int k = 0; k < 2; ++k) dst[m][k] = *(const PG8_LAS bf16x8*)(lds + PG8_SA(b, h) + aoff + m * 2048 + k * 1024); } while (0)
; #define PG8_LDB(dst, b, h) do { _Pragma("unroll") for (int n = 0; n < 2; ++n) _Pragma("unroll") for (int k = 0; k < 2; ++k) dst[n][k] = *(const PG8_LAS bf16x8*)(lds + PG8_SB(b, h) + boff + n * 2048 + k * 1024); } while (0)
; #define PG8_MMA(ai, bj, At, Bt) do { __builtin_amdgcn_s_setprio(1); _Pragma("unroll") for (int m = 0; m < 4; ++m) _Pragma("unroll") for (int n = 0; n < 2; ++n) _Pragma("unroll") for (int k = 0; k < 2; ++k) \
;         acc[ai][bj][m][n] = __builtin_amdgcn_mfma_f32_16x16x32_bf16(Bt[n][k], At[m][k], acc[ai][bj][m][n], 0, 0, 0); __builtin_amdgcn_s_setprio(0); } while (0)
; #define PG8_WAIT_V(n) asm volatile("s_waitcnt vmcnt(" #n ")" ::: "memory")
; #define PG8_WAIT_L(n) asm volatile("s_waitcnt lgkmcnt(" #n ")" ::: "memory")
; #define PG8_BAR __builtin_amdgcn_s_barrier()
; #define PG8_SCHED __builtin_amdgcn_sched_barrier(0)
; template <class Epi, class Sched, bool ALIGN_EPI = false, bool SP2 = false>
; __device__ __forceinline__ void gemm_phase(PG8_LAS unsigned char* lds, const Gemm g, const Sched& S, const Epi& E) {
;     ...
;             PG8_WAIT_V(8); PG8_WAIT_L(0); PG8_BAR; PG8_MMA(1, 0, At, B0); PG8_MMA(1, 1, At, B1); PG8_BAR; PG8_SCHED;
;             PG8_LDB(B0, 1, 0); PG8_LDB(B1, 1, 1); PG8_SCHED; PG8_LDA(At, 1, 0); PG8_STAGE(PG8_SA(0, 1), a2 + hstep, voffA);
;             PG8_WAIT_V(8); PG8_WAIT_L(0); PG8_BAR; PG8_MMA(0, 0, At, B0); PG8_MMA(0, 1, At, B1); PG8_BAR; PG8_SCHED;
	s_setprio 1
	s_waitcnt lgkmcnt(0)
	v_mfma_f32_16x16x32_bf16 v[60:63], v[144:147], v[188:191], v[60:63]
	v_mfma_f32_16x16x32_bf16 v[60:63], v[160:163], v[192:195], v[60:63]
	v_mfma_f32_16x16x32_bf16 v[56:59], v[164:167], v[188:191], v[56:59]
	v_mfma_f32_16x16x32_bf16 v[56:59], v[168:171], v[192:195], v[56:59]
	v_mfma_f32_16x16x32_bf16 v[40:43], v[164:167], v[196:199], v[40:43]
	v_mfma_f32_16x16x32_bf16 v[40:43], v[168:171], v[200:203], v[40:43]
	v_mfma_f32_16x16x32_bf16 v[44:47], v[144:147], v[196:199], v[44:47]
	v_mfma_f32_16x16x32_bf16 v[44:47], v[160:163], v[200:203], v[44:47]
	v_mfma_f32_16x16x32_bf16 v[28:31], v[144:147], v[204:207], v[28:31]
	v_mfma_f32_16x16x32_bf16 v[28:31], v[160:163], v[208:211], v[28:31]
	v_mfma_f32_16x16x32_bf16 v[24:27], v[164:167], v[204:207], v[24:27]
	v_mfma_f32_16x16x32_bf16 v[24:27], v[168:171], v[208:211], v[24:27]
	v_mfma_f32_16x16x32_bf16 v[8:11], v[164:167], v[212:215], v[8:11]
	v_mfma_f32_16x16x32_bf16 v[8:11], v[168:171], v[216:219], v[8:11]
	v_mfma_f32_16x16x32_bf16 v[12:15], v[144:147], v[212:215], v[12:15]
	v_mfma_f32_16x16x32_bf16 v[12:15], v[160:163], v[216:219], v[12:15]
	s_setprio 0
	s_setprio 1
	v_mfma_f32_16x16x32_bf16 v[52:55], v[172:175], v[188:191], v[52:55]
	v_mfma_f32_16x16x32_bf16 v[52:55], v[176:179], v[192:195], v[52:55]
	v_mfma_f32_16x16x32_bf16 v[48:51], v[180:183], v[188:191], v[48:51]
	v_mfma_f32_16x16x32_bf16 v[48:51], v[184:187], v[192:195], v[48:51]
	v_mfma_f32_16x16x32_bf16 v[32:35], v[180:183], v[196:199], v[32:35]
	v_mfma_f32_16x16x32_bf16 v[32:35], v[184:187], v[200:203], v[32:35]
	v_mfma_f32_16x16x32_bf16 v[36:39], v[172:175], v[196:199], v[36:39]
	v_mfma_f32_16x16x32_bf16 v[36:39], v[176:179], v[200:203], v[36:39]
	v_mfma_f32_16x16x32_bf16 v[20:23], v[172:175], v[204:207], v[20:23]
	v_mfma_f32_16x16x32_bf16 v[20:23], v[176:179], v[208:211], v[20:23]
	v_mfma_f32_16x16x32_bf16 v[16:19], v[180:183], v[204:207], v[16:19]
	v_mfma_f32_16x16x32_bf16 v[16:19], v[184:187], v[208:211], v[16:19]
	v_mfma_f32_16x16x32_bf16 v[0:3], v[180:183], v[212:215], v[0:3]
	v_mfma_f32_16x16x32_bf16 v[0:3], v[184:187], v[216:219], v[0:3]
	v_mfma_f32_16x16x32_bf16 v[4:7], v[172:175], v[212:215], v[4:7]
	v_mfma_f32_16x16x32_bf16 v[4:7], v[176:179], v[216:219], v[4:7]
	s_setprio 0
	s_barrier
	s_add_i32 s59, 0, 0x18000
	v_add_u32_e32 v159, s59, v153
	s_add_i32 s61, 0, 0x1c000
	ds_read_b128 v[144:147], v159
	ds_read_b128 v[160:163], v159 offset:1024
	ds_read_b128 v[164:167], v159 offset:2048
	ds_read_b128 v[168:171], v159 offset:3072
	v_add_u32_e32 v159, s61, v153
	ds_read_b128 v[172:175], v159
	ds_read_b128 v[176:179], v159 offset:1024
	ds_read_b128 v[180:183], v159 offset:2048
	ds_read_b128 v[184:187], v159 offset:3072
	s_add_u32 s42, s42, 0x160000
	s_addc_u32 s43, s43, 0
	s_mov_b32 m0, s44
	v_lshl_add_u64 v[228:229], s[42:43], 0, v[128:129]
	ds_read_b128 v[188:191], v157 offset:32768
	ds_read_b128 v[192:195], v157 offset:33792
	ds_read_b128 v[196:199], v157 offset:34816
	ds_read_b128 v[200:203], v157 offset:35840
	ds_read_b128 v[204:207], v157 offset:36864
	ds_read_b128 v[208:211], v157 offset:37888
	ds_read_b128 v[212:215], v157 offset:38912
	ds_read_b128 v[216:219], v157 offset:39936
	global_load_lds_dwordx4 v[228:229], off
	v_lshl_add_u64 v[228:229], s[42:43], 0, v[132:133]
	s_mov_b32 m0, s45
	s_nop 0
	global_load_lds_dwordx4 v[228:229], off
	s_waitcnt vmcnt(8)
	s_waitcnt lgkmcnt(0)
	s_barrier
	s_setprio 1
	s_waitcnt lgkmcnt(0)
	v_mfma_f32_16x16x32_bf16 v[124:127], v[144:147], v[188:191], v[124:127]
	v_mfma_f32_16x16x32_bf16 v[124:127], v[160:163], v[192:195], v[124:127]
	v_mfma_f32_16x16x32_bf16 v[120:123], v[164:167], v[188:191], v[120:123]
	v_mfma_f32_16x16x32_bf16 v[120:123], v[168:171], v[192:195], v[120:123]
	v_mfma_f32_16x16x32_bf16 v[104:107], v[164:167], v[196:199], v[104:107]
	v_mfma_f32_16x16x32_bf16 v[104:107], v[168:171], v[200:203], v[104:107]
	v_mfma_f32_16x16x32_bf16 v[108:111], v[144:147], v[196:199], v[108:111]
	v_mfma_f32_16x16x32_bf16 v[108:111], v[160:163], v[200:203], v[108:111]
	v_mfma_f32_16x16x32_bf16 v[92:95], v[144:147], v[204:207], v[92:95]
	v_mfma_f32_16x16x32_bf16 v[92:95], v[160:163], v[208:211], v[92:95]
	v_mfma_f32_16x16x32_bf16 v[88:91], v[164:167], v[204:207], v[88:91]
	v_mfma_f32_16x16x32_bf16 v[88:91], v[168:171], v[208:211], v[88:91]
	v_mfma_f32_16x16x32_bf16 v[72:75], v[164:167], v[212:215], v[72:75]
	v_mfma_f32_16x16x32_bf16 v[72:75], v[168:171], v[216:219], v[72:75]
	v_mfma_f32_16x16x32_bf16 v[76:79], v[144:147], v[212:215], v[76:79]
	v_mfma_f32_16x16x32_bf16 v[76:79], v[160:163], v[216:219], v[76:79]
	s_setprio 0
	s_setprio 1
	v_mfma_f32_16x16x32_bf16 v[116:119], v[172:175], v[188:191], v[116:119]
	v_mfma_f32_16x16x32_bf16 v[116:119], v[176:179], v[192:195], v[116:119]
	v_mfma_f32_16x16x32_bf16 v[112:115], v[180:183], v[188:191], v[112:115]
	v_mfma_f32_16x16x32_bf16 v[112:115], v[184:187], v[192:195], v[112:115]
	v_mfma_f32_16x16x32_bf16 v[96:99], v[180:183], v[196:199], v[96:99]
	v_mfma_f32_16x16x32_bf16 v[96:99], v[184:187], v[200:203], v[96:99]
	v_mfma_f32_16x16x32_bf16 v[100:103], v[172:175], v[196:199], v[100:103]
	v_mfma_f32_16x16x32_bf16 v[100:103], v[176:179], v[200:203], v[100:103]
	v_mfma_f32_16x16x32_bf16 v[84:87], v[172:175], v[204:207], v[84:87]
	v_mfma_f32_16x16x32_bf16 v[84:87], v[176:179], v[208:211], v[84:87]
	v_mfma_f32_16x16x32_bf16 v[80:83], v[180:183], v[204:207], v[80:83]
	v_mfma_f32_16x16x32_bf16 v[80:83], v[184:187], v[208:211], v[80:83]
	v_mfma_f32_16x16x32_bf16 v[64:67], v[180:183], v[212:215], v[64:67]
	v_mfma_f32_16x16x32_bf16 v[64:67], v[184:187], v[216:219], v[64:67]
	v_mfma_f32_16x16x32_bf16 v[68:71], v[172:175], v[212:215], v[68:71]
	v_mfma_f32_16x16x32_bf16 v[68:71], v[176:179], v[216:219], v[68:71]
	s_setprio 0
	s_barrier
; #define PG8_STAGE(bufoff, gbase, voff) do { _Pragma("unroll") for (int _i = 0; _i < 2; ++_i) \
;         __builtin_amdgcn_global_load_lds((const unsigned*)((const char*)(gbase) + (voff)[_i]), (PG8_LAS unsigned*)(lds + (bufoff) + ldsw + _i * 8192), 16, 0, 0); } while (0)
; #define PG8_LDA(dst, b, h) do { _Pragma("unroll") for (int m = 0; m < 4; ++m) _Pragma("unroll") for (int k = 0; k < 2; ++k) dst[m][k] = *(const PG8_LAS bf16x8*)(lds + PG8_SA(b, h) + aoff + m * 2048 + k * 1024); } while (0)
; #define PG8_MMA(ai, bj, At, Bt) do { __builtin_amdgcn_s_setprio(1); _Pragma("unroll") for (int m = 0; m < 4; ++m) _Pragma("unroll") for (int n = 0; n < 2; ++n) _Pragma("unroll") for (int k = 0; k < 2; ++k) \
;         acc[ai][bj][m][n] = __builtin_amdgcn_mfma_f32_16x16x32_bf16(Bt[n][k], At[m][k], acc[ai][bj][m][n], 0, 0, 0); __builtin_amdgcn_s_setprio(0); } while (0)
; #define PG8_WAIT_V(n) asm volatile("s_waitcnt vmcnt(" #n ")" ::: "memory")
; #define PG8_WAIT_L(n) asm volatile("s_waitcnt lgkmcnt(" #n ")" ::: "memory")
; #define PG8_BAR __builtin_amdgcn_s_barrier()
; #define PG8_SCHED __builtin_amdgcn_sched_barrier(0)
; template <class Epi, class Sched, bool ALIGN_EPI = false, bool SP2 = false>
; __device__ __forceinline__ void gemm_phase(PG8_LAS unsigned char* lds, const Gemm g, const Sched& S, const Epi& E) {
;     ...
;         for (int t = 0; t < nt; t += 2) {
;             const bool last = (t == nt - 2);
;     ...
;             PG8_WAIT_V(8); PG8_WAIT_L(0); PG8_BAR; PG8_MMA(0, 0, At, B0); PG8_MMA(0, 1, At, B1); PG8_BAR; PG8_SCHED;
;             PG8_LDA(At, 1, 1); PG8_STAGE(PG8_SB(1, 0), b3, voffB); PG8_STAGE(PG8_SB(1, 1), b3 + hstep, voffB); PG8_STAGE(PG8_SA(1, 0), a3, voffA);
;             PG8_WAIT_V(8); PG8_WAIT_L(0); PG8_BAR; PG8_MMA(1, 0, At, B0); PG8_MMA(1, 1, At, B1); PG8_BAR; PG8_SCHED;
	s_add_i32 s42, s59, s3
	v_lshl_add_u64 v[220:221], v[220:221], 0, s[16:17]
	s_mov_b32 m0, s42
	ds_read_b128 v[188:191], v157 offset:49152
	ds_read_b128 v[192:195], v157 offset:50176
	ds_read_b128 v[196:199], v157 offset:51200
	ds_read_b128 v[200:203], v157 offset:52224
	ds_read_b128 v[204:207], v157 offset:53248
	ds_read_b128 v[208:211], v157 offset:54272
	ds_read_b128 v[212:215], v157 offset:55296
	ds_read_b128 v[216:219], v157 offset:56320
	global_load_lds_dwordx4 v[220:221], off
	s_add_i32 m0, s42, 0x2000
	s_add_u32 s40, s40, 0x160080
	v_lshl_add_u64 v[220:221], v[222:223], 0, s[16:17]
	s_addc_u32 s41, s41, 0
	s_add_i32 s42, s61, s3
	global_load_lds_dwordx4 v[220:221], off
	v_lshl_add_u64 v[220:221], s[40:41], 0, v[130:131]
	s_mov_b32 m0, s42
	s_nop 0
	global_load_lds_dwordx4 v[220:221], off
	v_lshl_add_u64 v[220:221], s[40:41], 0, v[134:135]
	s_add_i32 m0, s42, 0x2000
	s_nop 0
	global_load_lds_dwordx4 v[220:221], off
	v_lshl_add_u64 v[220:221], v[224:225], 0, s[16:17]
	s_mov_b32 m0, s49
	s_nop 0
	global_load_lds_dwordx4 v[220:221], off
	v_lshl_add_u64 v[220:221], v[226:227], 0, s[16:17]
	s_mov_b32 m0, s50
	s_nop 0
	global_load_lds_dwordx4 v[220:221], off
	s_waitcnt vmcnt(8)
	s_waitcnt lgkmcnt(0)
	s_barrier
	s_setprio 1
	s_waitcnt lgkmcnt(0)
	v_mfma_f32_16x16x32_bf16 v[60:63], v[144:147], v[188:191], v[60:63]
	v_mfma_f32_16x16x32_bf16 v[60:63], v[160:163], v[192:195], v[60:63]
	v_mfma_f32_16x16x32_bf16 v[56:59], v[164:167], v[188:191], v[56:59]
	v_mfma_f32_16x16x32_bf16 v[56:59], v[168:171], v[192:195], v[56:59]
	v_mfma_f32_16x16x32_bf16 v[40:43], v[164:167], v[196:199], v[40:43]
	v_mfma_f32_16x16x32_bf16 v[40:43], v[168:171], v[200:203], v[40:43]
	v_mfma_f32_16x16x32_bf16 v[44:47], v[144:147], v[196:199], v[44:47]
	v_mfma_f32_16x16x32_bf16 v[44:47], v[160:163], v[200:203], v[44:47]
	v_mfma_f32_16x16x32_bf16 v[28:31], v[144:147], v[204:207], v[28:31]
	v_mfma_f32_16x16x32_bf16 v[28:31], v[160:163], v[208:211], v[28:31]
	v_mfma_f32_16x16x32_bf16 v[24:27], v[164:167], v[204:207], v[24:27]
	v_mfma_f32_16x16x32_bf16 v[24:27], v[168:171], v[208:211], v[24:27]
	v_mfma_f32_16x16x32_bf16 v[8:11], v[164:167], v[212:215], v[8:11]
	v_mfma_f32_16x16x32_bf16 v[8:11], v[168:171], v[216:219], v[8:11]
	v_mfma_f32_16x16x32_bf16 v[12:15], v[144:147], v[212:215], v[12:15]
	v_mfma_f32_16x16x32_bf16 v[12:15], v[160:163], v[216:219], v[12:15]
	s_setprio 0
	s_setprio 1
	v_mfma_f32_16x16x32_bf16 v[52:55], v[172:175], v[188:191], v[52:55]
	v_mfma_f32_16x16x32_bf16 v[52:55], v[176:179], v[192:195], v[52:55]
	v_mfma_f32_16x16x32_bf16 v[48:51], v[180:183], v[188:191], v[48:51]
	v_mfma_f32_16x16x32_bf16 v[48:51], v[184:187], v[192:195], v[48:51]
	v_mfma_f32_16x16x32_bf16 v[32:35], v[180:183], v[196:199], v[32:35]
	v_mfma_f32_16x16x32_bf16 v[32:35], v[184:187], v[200:203], v[32:35]
	v_mfma_f32_16x16x32_bf16 v[36:39], v[172:175], v[196:199], v[36:39]
	v_mfma_f32_16x16x32_bf16 v[36:39], v[176:179], v[200:203], v[36:39]
	v_mfma_f32_16x16x32_bf16 v[20:23], v[172:175], v[204:207], v[20:23]
	v_mfma_f32_16x16x32_bf16 v[20:23], v[176:179], v[208:211], v[20:23]
	v_mfma_f32_16x16x32_bf16 v[16:19], v[180:183], v[204:207], v[16:19]
	v_mfma_f32_16x16x32_bf16 v[16:19], v[184:187], v[208:211], v[16:19]
	v_mfma_f32_16x16x32_bf16 v[0:3], v[180:183], v[212:215], v[0:3]
	v_mfma_f32_16x16x32_bf16 v[0:3], v[184:187], v[216:219], v[0:3]
	v_mfma_f32_16x16x32_bf16 v[4:7], v[172:175], v[212:215], v[4:7]
	v_mfma_f32_16x16x32_bf16 v[4:7], v[176:179], v[216:219], v[4:7]
	s_setprio 0
	s_barrier
	s_add_i32 s58, s58, 2
	s_add_u32 s38, s38, 0x100
	s_addc_u32 s39, s39, 0
	s_add_u32 s11, s11, 0x100
	s_addc_u32 s57, s57, 0
	s_cmpk_gt_u32 s58, 0x55
	s_cbranch_scc0 .LBB0_779
	s_and_b64 vcc, exec, s[20:21]
	s_cbranch_vccz .LBB0_782
	s_barrier
